# S5 recurrence as 4 FMAs per step; gelu epilogue simplified algebraically; fewer waitcnts in the C-projection
# baseline (speedup 1.0000x reference)
; DI void s5_pass1_item(const Params& P, int bitem, unsigned char* smem) {
;     ...
;     float xr = 0.f, xi = 0.f;
;     bf16x8 ubs[4];
; #pragma unroll
;     for (int sub = 0; sub < 4; ++sub) ubs[sub] = *(const bf16x8*)(ubase + (size_t)(sub * 16 + r) * NPROJ + 8 * (q & 1));
; #pragma unroll
;     for (int sub = 0; sub < 4; ++sub) {
;         s5_bu16(ubs[sub], af, buf, r, q);
;         asm volatile("s_waitcnt lgkmcnt(0)" ::: "memory");
; #pragma unroll
;         for (int tt = 0; tt < 16; ++tt) { const float bur = buf[lane * 17 + tt], bui = buf[(64 + lane) * 17 + tt];
;             const float nxr = ab[0] * xr - ab[1] * xi + bur, nxi = ab[0] * xi + ab[1] * xr + bui; xr = nxr; xi = nxi; }
;         asm volatile("s_waitcnt lgkmcnt(0)" ::: "memory");
;     }
.Ls5p1_round:
	s_waitcnt vmcnt(1)
	v_mov_b32_e32 v88, v120
	v_mov_b32_e32 v89, v121
	v_mov_b32_e32 v90, v122
	v_mov_b32_e32 v91, v123
	v_mov_b32_e32 v92, v124
	v_mov_b32_e32 v93, v125
	v_mov_b32_e32 v94, v126
	v_mov_b32_e32 v95, v127
	v_mov_b32_e32 v96, v128
	v_mov_b32_e32 v97, v129
	v_mov_b32_e32 v98, v130
	v_mov_b32_e32 v99, v131
	v_mov_b32_e32 v100, v132
	v_mov_b32_e32 v101, v133
	v_mov_b32_e32 v102, v134
	v_mov_b32_e32 v103, v135
	s_add_u32 s28, s28, 0xf00000
	s_addc_u32 s29, s29, 0
	s_add_u32 s40, s28, 0x0
	s_addc_u32 s41, s29, 0
	s_add_u32 s42, s28, 0x1e000
	s_addc_u32 s43, s29, 0
	s_add_u32 s44, s28, 0x3c000
	s_addc_u32 s45, s29, 0
	s_add_u32 s46, s28, 0x5a000
	s_addc_u32 s47, s29, 0
	global_load_dwordx4 v[120:123], v83, s[40:41]
	global_load_dwordx4 v[124:127], v83, s[42:43]
	global_load_dwordx4 v[128:131], v83, s[44:45]
	global_load_dwordx4 v[132:135], v83, s[46:47]
	v_mov_b32_e32 v192, 0
	v_mov_b32_e32 v193, 0
	v_mfma_f32_16x16x32_bf16 v[160:163], v[88:91], v[8:11], 0
	v_mfma_f32_16x16x32_bf16 v[164:167], v[88:91], v[12:15], 0
	v_mfma_f32_16x16x32_bf16 v[168:171], v[88:91], v[16:19], 0
	v_mfma_f32_16x16x32_bf16 v[172:175], v[88:91], v[20:23], 0
	v_mfma_f32_16x16x32_bf16 v[176:179], v[88:91], v[24:27], 0
	v_mfma_f32_16x16x32_bf16 v[180:183], v[88:91], v[28:31], 0
	v_mfma_f32_16x16x32_bf16 v[184:187], v[88:91], v[32:35], 0
	v_mfma_f32_16x16x32_bf16 v[188:191], v[88:91], v[36:39], 0
	s_nop 7
	v_permlane32_swap_b32_e32 v160, v168
	v_permlane32_swap_b32_e32 v161, v169
	v_permlane32_swap_b32_e32 v162, v170
	v_permlane32_swap_b32_e32 v163, v171
	v_permlane32_swap_b32_e32 v164, v172
	v_permlane32_swap_b32_e32 v165, v173
	v_permlane32_swap_b32_e32 v166, v174
	v_permlane32_swap_b32_e32 v167, v175
	v_permlane32_swap_b32_e32 v176, v184
	v_permlane32_swap_b32_e32 v177, v185
	v_permlane32_swap_b32_e32 v178, v186
	v_permlane32_swap_b32_e32 v179, v187
	v_permlane32_swap_b32_e32 v180, v188
	v_permlane32_swap_b32_e32 v181, v189
	v_permlane32_swap_b32_e32 v182, v190
	v_permlane32_swap_b32_e32 v183, v191
	v_permlane16_swap_b32_e32 v160, v164
	v_permlane16_swap_b32_e32 v161, v165
	v_permlane16_swap_b32_e32 v162, v166
	v_permlane16_swap_b32_e32 v163, v167
	v_permlane16_swap_b32_e32 v168, v172
	v_permlane16_swap_b32_e32 v169, v173
	v_permlane16_swap_b32_e32 v170, v174
	v_permlane16_swap_b32_e32 v171, v175
	v_permlane16_swap_b32_e32 v176, v180
	v_permlane16_swap_b32_e32 v177, v181
	v_permlane16_swap_b32_e32 v178, v182
	v_permlane16_swap_b32_e32 v179, v183
	v_permlane16_swap_b32_e32 v184, v188
	v_permlane16_swap_b32_e32 v185, v189
	v_permlane16_swap_b32_e32 v186, v190
	v_permlane16_swap_b32_e32 v187, v191
	v_fma_f32 v194, -v73, v193, v160
	v_fma_f32 v195, v73, v192, v176
	v_fma_f32 v192, v72, v192, v194
	v_fma_f32 v193, v72, v193, v195
	v_fma_f32 v194, -v73, v193, v161
	v_fma_f32 v195, v73, v192, v177
	v_fma_f32 v192, v72, v192, v194
	v_fma_f32 v193, v72, v193, v195
	v_fma_f32 v194, -v73, v193, v162
	v_fma_f32 v195, v73, v192, v178
	v_fma_f32 v192, v72, v192, v194
	v_fma_f32 v193, v72, v193, v195
	v_fma_f32 v194, -v73, v193, v163
	v_fma_f32 v195, v73, v192, v179
	v_fma_f32 v192, v72, v192, v194
	v_fma_f32 v193, v72, v193, v195
	v_fma_f32 v194, -v73, v193, v164
	v_fma_f32 v195, v73, v192, v180
	v_fma_f32 v192, v72, v192, v194
	v_fma_f32 v193, v72, v193, v195
	v_fma_f32 v194, -v73, v193, v165
	v_fma_f32 v195, v73, v192, v181
	v_fma_f32 v192, v72, v192, v194
	v_fma_f32 v193, v72, v193, v195
	v_fma_f32 v194, -v73, v193, v166
	v_fma_f32 v195, v73, v192, v182
	v_fma_f32 v192, v72, v192, v194
	v_fma_f32 v193, v72, v193, v195
	v_fma_f32 v194, -v73, v193, v167
	v_fma_f32 v195, v73, v192, v183
	v_fma_f32 v192, v72, v192, v194
	v_fma_f32 v193, v72, v193, v195
	v_fma_f32 v194, -v73, v193, v168
	v_fma_f32 v195, v73, v192, v184
	v_fma_f32 v192, v72, v192, v194
	v_fma_f32 v193, v72, v193, v195
	v_fma_f32 v194, -v73, v193, v169
	v_fma_f32 v195, v73, v192, v185
	v_fma_f32 v192, v72, v192, v194
	v_fma_f32 v193, v72, v193, v195
	v_fma_f32 v194, -v73, v193, v170
	v_fma_f32 v195, v73, v192, v186
	v_fma_f32 v192, v72, v192, v194
	v_fma_f32 v193, v72, v193, v195
	v_fma_f32 v194, -v73, v193, v171
	v_fma_f32 v195, v73, v192, v187
	v_fma_f32 v192, v72, v192, v194
	v_fma_f32 v193, v72, v193, v195
	v_fma_f32 v194, -v73, v193, v172
	v_fma_f32 v195, v73, v192, v188
	v_fma_f32 v192, v72, v192, v194
	v_fma_f32 v193, v72, v193, v195
	v_fma_f32 v194, -v73, v193, v173
	v_fma_f32 v195, v73, v192, v189
	v_fma_f32 v192, v72, v192, v194
	v_fma_f32 v193, v72, v193, v195
	v_fma_f32 v194, -v73, v193, v174
	v_fma_f32 v195, v73, v192, v190
	v_fma_f32 v192, v72, v192, v194
	v_fma_f32 v193, v72, v193, v195
	v_fma_f32 v194, -v73, v193, v175
	v_fma_f32 v195, v73, v192, v191
	v_fma_f32 v192, v72, v192, v194
	v_fma_f32 v193, v72, v193, v195
	v_mfma_f32_16x16x32_bf16 v[160:163], v[92:95], v[8:11], 0
	v_mfma_f32_16x16x32_bf16 v[164:167], v[92:95], v[12:15], 0
	v_mfma_f32_16x16x32_bf16 v[168:171], v[92:95], v[16:19], 0
	v_mfma_f32_16x16x32_bf16 v[172:175], v[92:95], v[20:23], 0
	v_mfma_f32_16x16x32_bf16 v[176:179], v[92:95], v[24:27], 0
	v_mfma_f32_16x16x32_bf16 v[180:183], v[92:95], v[28:31], 0
	v_mfma_f32_16x16x32_bf16 v[184:187], v[92:95], v[32:35], 0
	v_mfma_f32_16x16x32_bf16 v[188:191], v[92:95], v[36:39], 0
	s_nop 7
	v_permlane32_swap_b32_e32 v160, v168
	v_permlane32_swap_b32_e32 v161, v169
	v_permlane32_swap_b32_e32 v162, v170
	v_permlane32_swap_b32_e32 v163, v171
	v_permlane32_swap_b32_e32 v164, v172
	v_permlane32_swap_b32_e32 v165, v173
	v_permlane32_swap_b32_e32 v166, v174
	v_permlane32_swap_b32_e32 v167, v175
	v_permlane32_swap_b32_e32 v176, v184
	v_permlane32_swap_b32_e32 v177, v185
; DI void s5_bu16(const bf16x8 ub, const bf16x8 (&af)[8], float* buf, int r, int q) {
; #pragma unroll
;     for (int pt = 0; pt < 8; ++pt) { f32x4 d = {0.f, 0.f, 0.f, 0.f}; d = __builtin_amdgcn_mfma_f32_16x16x32_bf16(af[pt], ub, d, 0, 0, 0);
; #pragma unroll
;         for (int j = 0; j < 4; ++j) buf[(16 * pt + 4 * q + j) * 17 + r] = d[j]; }
; DI void s5_pass1_item(const Params& P, int bitem, unsigned char* smem) {
;     ...
;     for (int sub = 0; sub < 4; ++sub) {
;         s5_bu16(ubs[sub], af, buf, r, q);
;         asm volatile("s_waitcnt lgkmcnt(0)" ::: "memory");
; #pragma unroll
;         for (int tt = 0; tt < 16; ++tt) { const float bur = buf[lane * 17 + tt], bui = buf[(64 + lane) * 17 + tt];
;             const float nxr = ab[0] * xr - ab[1] * xi + bur, nxi = ab[0] * xi + ab[1] * xr + bui; xr = nxr; xi = nxi; }
	v_permlane32_swap_b32_e32 v178, v186
	v_permlane32_swap_b32_e32 v179, v187
	v_permlane32_swap_b32_e32 v180, v188
	v_permlane32_swap_b32_e32 v181, v189
	v_permlane32_swap_b32_e32 v182, v190
	v_permlane32_swap_b32_e32 v183, v191
	v_permlane16_swap_b32_e32 v160, v164
	v_permlane16_swap_b32_e32 v161, v165
	v_permlane16_swap_b32_e32 v162, v166
	v_permlane16_swap_b32_e32 v163, v167
	v_permlane16_swap_b32_e32 v168, v172
	v_permlane16_swap_b32_e32 v169, v173
	v_permlane16_swap_b32_e32 v170, v174
	v_permlane16_swap_b32_e32 v171, v175
	v_permlane16_swap_b32_e32 v176, v180
	v_permlane16_swap_b32_e32 v177, v181
	v_permlane16_swap_b32_e32 v178, v182
	v_permlane16_swap_b32_e32 v179, v183
	v_permlane16_swap_b32_e32 v184, v188
	v_permlane16_swap_b32_e32 v185, v189
	v_permlane16_swap_b32_e32 v186, v190
	v_permlane16_swap_b32_e32 v187, v191
	v_fma_f32 v194, -v73, v193, v160
	v_fma_f32 v195, v73, v192, v176
	v_fma_f32 v192, v72, v192, v194
	v_fma_f32 v193, v72, v193, v195
	v_fma_f32 v194, -v73, v193, v161
	v_fma_f32 v195, v73, v192, v177
	v_fma_f32 v192, v72, v192, v194
	v_fma_f32 v193, v72, v193, v195
	v_fma_f32 v194, -v73, v193, v162
	v_fma_f32 v195, v73, v192, v178
	v_fma_f32 v192, v72, v192, v194
	v_fma_f32 v193, v72, v193, v195
	v_fma_f32 v194, -v73, v193, v163
	v_fma_f32 v195, v73, v192, v179
	v_fma_f32 v192, v72, v192, v194
	v_fma_f32 v193, v72, v193, v195
	v_fma_f32 v194, -v73, v193, v164
	v_fma_f32 v195, v73, v192, v180
	v_fma_f32 v192, v72, v192, v194
	v_fma_f32 v193, v72, v193, v195
	v_fma_f32 v194, -v73, v193, v165
	v_fma_f32 v195, v73, v192, v181
	v_fma_f32 v192, v72, v192, v194
	v_fma_f32 v193, v72, v193, v195
	v_fma_f32 v194, -v73, v193, v166
	v_fma_f32 v195, v73, v192, v182
	v_fma_f32 v192, v72, v192, v194
	v_fma_f32 v193, v72, v193, v195
	v_fma_f32 v194, -v73, v193, v167
	v_fma_f32 v195, v73, v192, v183
	v_fma_f32 v192, v72, v192, v194
	v_fma_f32 v193, v72, v193, v195
	v_fma_f32 v194, -v73, v193, v168
	v_fma_f32 v195, v73, v192, v184
	v_fma_f32 v192, v72, v192, v194
	v_fma_f32 v193, v72, v193, v195
	v_fma_f32 v194, -v73, v193, v169
	v_fma_f32 v195, v73, v192, v185
	v_fma_f32 v192, v72, v192, v194
	v_fma_f32 v193, v72, v193, v195
	v_fma_f32 v194, -v73, v193, v170
	v_fma_f32 v195, v73, v192, v186
	v_fma_f32 v192, v72, v192, v194
	v_fma_f32 v193, v72, v193, v195
	v_fma_f32 v194, -v73, v193, v171
	v_fma_f32 v195, v73, v192, v187
	v_fma_f32 v192, v72, v192, v194
	v_fma_f32 v193, v72, v193, v195
	v_fma_f32 v194, -v73, v193, v172
	v_fma_f32 v195, v73, v192, v188
	v_fma_f32 v192, v72, v192, v194
	v_fma_f32 v193, v72, v193, v195
	v_fma_f32 v194, -v73, v193, v173
	v_fma_f32 v195, v73, v192, v189
	v_fma_f32 v192, v72, v192, v194
	v_fma_f32 v193, v72, v193, v195
	v_fma_f32 v194, -v73, v193, v174
	v_fma_f32 v195, v73, v192, v190
	v_fma_f32 v192, v72, v192, v194
	v_fma_f32 v193, v72, v193, v195
	v_fma_f32 v194, -v73, v193, v175
	v_fma_f32 v195, v73, v192, v191
	v_fma_f32 v192, v72, v192, v194
	v_fma_f32 v193, v72, v193, v195
	v_mfma_f32_16x16x32_bf16 v[160:163], v[96:99], v[8:11], 0
	v_mfma_f32_16x16x32_bf16 v[164:167], v[96:99], v[12:15], 0
	v_mfma_f32_16x16x32_bf16 v[168:171], v[96:99], v[16:19], 0
	v_mfma_f32_16x16x32_bf16 v[172:175], v[96:99], v[20:23], 0
	v_mfma_f32_16x16x32_bf16 v[176:179], v[96:99], v[24:27], 0
	v_mfma_f32_16x16x32_bf16 v[180:183], v[96:99], v[28:31], 0
	v_mfma_f32_16x16x32_bf16 v[184:187], v[96:99], v[32:35], 0
	v_mfma_f32_16x16x32_bf16 v[188:191], v[96:99], v[36:39], 0
	s_nop 7
	v_permlane32_swap_b32_e32 v160, v168
	v_permlane32_swap_b32_e32 v161, v169
	v_permlane32_swap_b32_e32 v162, v170
	v_permlane32_swap_b32_e32 v163, v171
	v_permlane32_swap_b32_e32 v164, v172
	v_permlane32_swap_b32_e32 v165, v173
	v_permlane32_swap_b32_e32 v166, v174
	v_permlane32_swap_b32_e32 v167, v175
	v_permlane32_swap_b32_e32 v176, v184
	v_permlane32_swap_b32_e32 v177, v185
	v_permlane32_swap_b32_e32 v178, v186
	v_permlane32_swap_b32_e32 v179, v187
	v_permlane32_swap_b32_e32 v180, v188
	v_permlane32_swap_b32_e32 v181, v189
	v_permlane32_swap_b32_e32 v182, v190
	v_permlane32_swap_b32_e32 v183, v191
	v_permlane16_swap_b32_e32 v160, v164
	v_permlane16_swap_b32_e32 v161, v165
	v_permlane16_swap_b32_e32 v162, v166
	v_permlane16_swap_b32_e32 v163, v167
	v_permlane16_swap_b32_e32 v168, v172
	v_permlane16_swap_b32_e32 v169, v173
	v_permlane16_swap_b32_e32 v170, v174
	v_permlane16_swap_b32_e32 v171, v175
	v_permlane16_swap_b32_e32 v176, v180
	v_permlane16_swap_b32_e32 v177, v181
	v_permlane16_swap_b32_e32 v178, v182
	v_permlane16_swap_b32_e32 v179, v183
	v_permlane16_swap_b32_e32 v184, v188
	v_permlane16_swap_b32_e32 v185, v189
	v_permlane16_swap_b32_e32 v186, v190
	v_permlane16_swap_b32_e32 v187, v191
	v_fma_f32 v194, -v73, v193, v160
	v_fma_f32 v195, v73, v192, v176
	v_fma_f32 v192, v72, v192, v194
	v_fma_f32 v193, v72, v193, v195
	v_fma_f32 v194, -v73, v193, v161
	v_fma_f32 v195, v73, v192, v177
	v_fma_f32 v192, v72, v192, v194
	v_fma_f32 v193, v72, v193, v195
	v_fma_f32 v194, -v73, v193, v162
	v_fma_f32 v195, v73, v192, v178
	v_fma_f32 v192, v72, v192, v194
	v_fma_f32 v193, v72, v193, v195
	v_fma_f32 v194, -v73, v193, v163
	v_fma_f32 v195, v73, v192, v179
	v_fma_f32 v192, v72, v192, v194
	v_fma_f32 v193, v72, v193, v195
	v_fma_f32 v194, -v73, v193, v164
	v_fma_f32 v195, v73, v192, v180
	v_fma_f32 v192, v72, v192, v194
	v_fma_f32 v193, v72, v193, v195
	v_fma_f32 v194, -v73, v193, v165
	v_fma_f32 v195, v73, v192, v181
	v_fma_f32 v192, v72, v192, v194
; DI void s5_pass1_item(const Params& P, int bitem, unsigned char* smem) {
;     ...
;     for (int sub = 0; sub < 4; ++sub) {
;         s5_bu16(ubs[sub], af, buf, r, q);
;         asm volatile("s_waitcnt lgkmcnt(0)" ::: "memory");
; #pragma unroll
;         for (int tt = 0; tt < 16; ++tt) { const float bur = buf[lane * 17 + tt], bui = buf[(64 + lane) * 17 + tt];
;             const float nxr = ab[0] * xr - ab[1] * xi + bur, nxi = ab[0] * xi + ab[1] * xr + bui; xr = nxr; xi = nxi; }
;         asm volatile("s_waitcnt lgkmcnt(0)" ::: "memory");
;     }
;     f32x2_t e = {xr, xi};
;     *(f32x2_t*)(ws + WS_S5END + ((size_t)((b * 64 + grp) * 32 + ch) * 64 + lane) * 8) = e;
	v_fma_f32 v193, v72, v193, v195
	v_fma_f32 v194, -v73, v193, v166
	v_fma_f32 v195, v73, v192, v182
	v_fma_f32 v192, v72, v192, v194
	v_fma_f32 v193, v72, v193, v195
	v_fma_f32 v194, -v73, v193, v167
	v_fma_f32 v195, v73, v192, v183
	v_fma_f32 v192, v72, v192, v194
	v_fma_f32 v193, v72, v193, v195
	v_fma_f32 v194, -v73, v193, v168
	v_fma_f32 v195, v73, v192, v184
	v_fma_f32 v192, v72, v192, v194
	v_fma_f32 v193, v72, v193, v195
	v_fma_f32 v194, -v73, v193, v169
	v_fma_f32 v195, v73, v192, v185
	v_fma_f32 v192, v72, v192, v194
	v_fma_f32 v193, v72, v193, v195
	v_fma_f32 v194, -v73, v193, v170
	v_fma_f32 v195, v73, v192, v186
	v_fma_f32 v192, v72, v192, v194
	v_fma_f32 v193, v72, v193, v195
	v_fma_f32 v194, -v73, v193, v171
	v_fma_f32 v195, v73, v192, v187
	v_fma_f32 v192, v72, v192, v194
	v_fma_f32 v193, v72, v193, v195
	v_fma_f32 v194, -v73, v193, v172
	v_fma_f32 v195, v73, v192, v188
	v_fma_f32 v192, v72, v192, v194
	v_fma_f32 v193, v72, v193, v195
	v_fma_f32 v194, -v73, v193, v173
	v_fma_f32 v195, v73, v192, v189
	v_fma_f32 v192, v72, v192, v194
	v_fma_f32 v193, v72, v193, v195
	v_fma_f32 v194, -v73, v193, v174
	v_fma_f32 v195, v73, v192, v190
	v_fma_f32 v192, v72, v192, v194
	v_fma_f32 v193, v72, v193, v195
	v_fma_f32 v194, -v73, v193, v175
	v_fma_f32 v195, v73, v192, v191
	v_fma_f32 v192, v72, v192, v194
	v_fma_f32 v193, v72, v193, v195
	v_mfma_f32_16x16x32_bf16 v[160:163], v[100:103], v[8:11], 0
	v_mfma_f32_16x16x32_bf16 v[164:167], v[100:103], v[12:15], 0
	v_mfma_f32_16x16x32_bf16 v[168:171], v[100:103], v[16:19], 0
	v_mfma_f32_16x16x32_bf16 v[172:175], v[100:103], v[20:23], 0
	v_mfma_f32_16x16x32_bf16 v[176:179], v[100:103], v[24:27], 0
	v_mfma_f32_16x16x32_bf16 v[180:183], v[100:103], v[28:31], 0
	v_mfma_f32_16x16x32_bf16 v[184:187], v[100:103], v[32:35], 0
	v_mfma_f32_16x16x32_bf16 v[188:191], v[100:103], v[36:39], 0
	s_nop 7
	v_permlane32_swap_b32_e32 v160, v168
	v_permlane32_swap_b32_e32 v161, v169
	v_permlane32_swap_b32_e32 v162, v170
	v_permlane32_swap_b32_e32 v163, v171
	v_permlane32_swap_b32_e32 v164, v172
	v_permlane32_swap_b32_e32 v165, v173
	v_permlane32_swap_b32_e32 v166, v174
	v_permlane32_swap_b32_e32 v167, v175
	v_permlane32_swap_b32_e32 v176, v184
	v_permlane32_swap_b32_e32 v177, v185
	v_permlane32_swap_b32_e32 v178, v186
	v_permlane32_swap_b32_e32 v179, v187
	v_permlane32_swap_b32_e32 v180, v188
	v_permlane32_swap_b32_e32 v181, v189
	v_permlane32_swap_b32_e32 v182, v190
	v_permlane32_swap_b32_e32 v183, v191
	v_permlane16_swap_b32_e32 v160, v164
	v_permlane16_swap_b32_e32 v161, v165
	v_permlane16_swap_b32_e32 v162, v166
	v_permlane16_swap_b32_e32 v163, v167
	v_permlane16_swap_b32_e32 v168, v172
	v_permlane16_swap_b32_e32 v169, v173
	v_permlane16_swap_b32_e32 v170, v174
	v_permlane16_swap_b32_e32 v171, v175
	v_permlane16_swap_b32_e32 v176, v180
	v_permlane16_swap_b32_e32 v177, v181
	v_permlane16_swap_b32_e32 v178, v182
	v_permlane16_swap_b32_e32 v179, v183
	v_permlane16_swap_b32_e32 v184, v188
	v_permlane16_swap_b32_e32 v185, v189
	v_permlane16_swap_b32_e32 v186, v190
	v_permlane16_swap_b32_e32 v187, v191
	v_fma_f32 v194, -v73, v193, v160
	v_fma_f32 v195, v73, v192, v176
	v_fma_f32 v192, v72, v192, v194
	v_fma_f32 v193, v72, v193, v195
	v_fma_f32 v194, -v73, v193, v161
	v_fma_f32 v195, v73, v192, v177
	v_fma_f32 v192, v72, v192, v194
	v_fma_f32 v193, v72, v193, v195
	v_fma_f32 v194, -v73, v193, v162
	v_fma_f32 v195, v73, v192, v178
	v_fma_f32 v192, v72, v192, v194
	v_fma_f32 v193, v72, v193, v195
	v_fma_f32 v194, -v73, v193, v163
	v_fma_f32 v195, v73, v192, v179
	v_fma_f32 v192, v72, v192, v194
	v_fma_f32 v193, v72, v193, v195
	v_fma_f32 v194, -v73, v193, v164
	v_fma_f32 v195, v73, v192, v180
	v_fma_f32 v192, v72, v192, v194
	v_fma_f32 v193, v72, v193, v195
	v_fma_f32 v194, -v73, v193, v165
	v_fma_f32 v195, v73, v192, v181
	v_fma_f32 v192, v72, v192, v194
	v_fma_f32 v193, v72, v193, v195
	v_fma_f32 v194, -v73, v193, v166
	v_fma_f32 v195, v73, v192, v182
	v_fma_f32 v192, v72, v192, v194
	v_fma_f32 v193, v72, v193, v195
	v_fma_f32 v194, -v73, v193, v167
	v_fma_f32 v195, v73, v192, v183
	v_fma_f32 v192, v72, v192, v194
	v_fma_f32 v193, v72, v193, v195
	v_fma_f32 v194, -v73, v193, v168
	v_fma_f32 v195, v73, v192, v184
	v_fma_f32 v192, v72, v192, v194
	v_fma_f32 v193, v72, v193, v195
	v_fma_f32 v194, -v73, v193, v169
	v_fma_f32 v195, v73, v192, v185
	v_fma_f32 v192, v72, v192, v194
	v_fma_f32 v193, v72, v193, v195
	v_fma_f32 v194, -v73, v193, v170
	v_fma_f32 v195, v73, v192, v186
	v_fma_f32 v192, v72, v192, v194
	v_fma_f32 v193, v72, v193, v195
	v_fma_f32 v194, -v73, v193, v171
	v_fma_f32 v195, v73, v192, v187
	v_fma_f32 v192, v72, v192, v194
	v_fma_f32 v193, v72, v193, v195
	v_fma_f32 v194, -v73, v193, v172
	v_fma_f32 v195, v73, v192, v188
	v_fma_f32 v192, v72, v192, v194
	v_fma_f32 v193, v72, v193, v195
	v_fma_f32 v194, -v73, v193, v173
	v_fma_f32 v195, v73, v192, v189
	v_fma_f32 v192, v72, v192, v194
	v_fma_f32 v193, v72, v193, v195
	v_fma_f32 v194, -v73, v193, v174
	v_fma_f32 v195, v73, v192, v190
	v_fma_f32 v192, v72, v192, v194
	v_fma_f32 v193, v72, v193, v195
	v_fma_f32 v194, -v73, v193, v175
	v_fma_f32 v195, v73, v192, v191
	v_fma_f32 v192, v72, v192, v194
	v_fma_f32 v193, v72, v193, v195
	global_store_dwordx2 v84, v[192:193], s[30:31]
	s_add_u32 s30, s30, 0x100000
	s_addc_u32 s31, s31, 0
	s_add_i32 s26, s26, 1
	s_cmp_lt_u32 s26, 8
	s_cbranch_scc1 .Ls5p1_round
	s_waitcnt vmcnt(0)
	s_branch .LBB0_654

; DI void s5_pass3_item(const Params& P, int bitem, unsigned char* smem) {
;     int tid_ = threadIdx.x; asm volatile("" : "+v"(tid_));
;     unsigned char* ws = P.ws; const int tid = tid_, wid = tid >> 6, lane = tid & 63, r = lane & 15, q = lane >> 4;
;     const int item = bitem * 8 + wid, ch = item & 31, grp = (item >> 5) & 63, b = item >> 11;
;     const bf16_t* proj = (const bf16_t*)(ws + WS_PROJ); const float* sm = (const float*)(ws + WS_SMALL);
;     float* xs = (float*)smem + wid * 2176;
;     bf16_t* HG = (bf16_t*)(ws + WS_HG);
;     const bf16_t* tb = (const bf16_t*)(sm + SM_BB);
;     bf16x8 af[8];
; #pragma unroll
;     for (int pt = 0; pt < 8; ++pt) af[pt] = *(const bf16x8*)(tb + (grp * 128 + 16 * pt + r) * 32 + 8 * q);
;     const f32x4 ab = *(const f32x4*)(sm + SM_AB + (grp * 64 + lane) * 4);
;     float cB[32];
;     { const float* cre = P.in[21] + (size_t)(grp * 16 + r) * 64; const float* cim = P.in[22] + (size_t)(grp * 16 + r) * 64;
; #pragma unroll
;       for (int i = 0; i < 32; ++i) { const int k = 4 * i + q; cB[i] = (i < 16) ? cre[k] : -cim[k - 64]; } }
;     const float dsk = P.in[23][grp * 16 + r];
;     const bf16_t* ubase = proj + (size_t)(b * TT + ch * 64) * NPROJ + C_SSM + grp * 16;
;     bf16x8 ubs[4]; unsigned short uvs[4][4];
; #pragma unroll
;     for (int sub = 0; sub < 4; ++sub) { ubs[sub] = *(const bf16x8*)(ubase + (size_t)(sub * 16 + r) * NPROJ + 8 * (q & 1));
; #pragma unroll
;         for (int j = 0; j < 4; ++j) uvs[sub][j] = ubase[(size_t)(sub * 16 + 4 * q + j) * NPROJ + r]; }
.Ls5n_start:
	v_lshrrev_b32_e32 v1, 6, v206
	v_and_b32_e32 v2, 63, v206
	v_readfirstlane_b32 s16, v1
	v_and_b32_e32 v3, 15, v206
	v_bfe_u32 v4, v206, 4, 2
	s_lshr_b32 s17, s88, 2
	s_and_b32 s18, s88, 3
	s_lshl_b32 s18, s18, 3
	s_add_i32 s18, s18, s16
	v_mov_b32_e32 v80, 0x3dd2d3e8
	v_mov_b32_e32 v205, 0x40135761
	s_mul_i32 s0, s16, 0x2200
	s_mov_b32 m0, s0
	v_mul_u32_u24_e32 v5, 0x210, v3
	v_lshl_add_u32 v5, v4, 4, v5
	v_add_u32_e32 v77, s0, v5
	v_lshlrev_b32_e32 v5, 2, v1
	v_add_u32_e32 v78, 0x19000, v5
	v_and_b32_e32 v5, 7, v2
	v_lshlrev_b32_e32 v5, 2, v5
	v_add_u32_e32 v79, 0x19000, v5
	v_lshlrev_b32_e32 v5, 3, v206
	v_add_u32_e32 v81, 0x11000, v5
	v_add_u32_e32 v199, 0x1000, v5
	v_add_u32_e32 v204, 0x3000, v5
	v_lshlrev_b32_e32 v5, 3, v2
	v_add_u32_e32 v82, 0x11000, v5
	v_and_b32_e32 v5, 1, v4
	v_lshlrev_b32_e32 v5, 4, v5
	s_movk_i32 s1, 0x1e00
	v_mad_u32_u24 v83, v3, s1, v5
	v_lshlrev_b32_e32 v5, 2, v4
	v_lshlrev_b32_e32 v6, 1, v3
	v_mad_u32_u24 v84, v5, s1, v6
	v_add_u32_e32 v85, 0x1e00, v84
	v_add_u32_e32 v86, 0x3c00, v84
	v_add_u32_e32 v87, 0x5a00, v84
	v_lshlrev_b32_e32 v7, 13, v4
	v_add_u32_e32 v7, v7, v6
	v_add_u32_e32 v198, 0x1000, v7
	s_lshl_b32 s2, s17, 13
	s_add_u32 s0, s74, 0x9f20400
	s_addc_u32 s1, s75, 0
	s_add_u32 s0, s0, s2
	s_addc_u32 s1, s1, 0
	s_add_u32 s2, s0, 0x1000
	s_addc_u32 s3, s1, 0
	v_lshlrev_b32_e32 v5, 6, v3
	v_lshl_add_u32 v5, v4, 4, v5
	global_load_dwordx4 v[8:11], v5, s[0:1] offset:0
	global_load_dwordx4 v[12:15], v5, s[0:1] offset:1024
	global_load_dwordx4 v[16:19], v5, s[0:1] offset:2048
	global_load_dwordx4 v[20:23], v5, s[0:1] offset:3072
	global_load_dwordx4 v[24:27], v5, s[2:3] offset:0
	global_load_dwordx4 v[28:31], v5, s[2:3] offset:1024
	global_load_dwordx4 v[32:35], v5, s[2:3] offset:2048
	global_load_dwordx4 v[36:39], v5, s[2:3] offset:3072
	s_lshl_b32 s6, s17, 10
	s_add_u32 s4, s74, 0x9f10400
	s_addc_u32 s5, s75, 0
	s_add_u32 s4, s4, s6
	s_addc_u32 s5, s5, 0
	v_lshlrev_b32_e32 v6, 4, v2
	global_load_dwordx4 v[72:75], v6, s[4:5]
	s_lshl_b32 s6, s17, 12
	s_add_u32 s8, s62, s6
	s_addc_u32 s9, s63, 0
	s_add_u32 s10, s64, s6
	s_addc_u32 s11, s65, 0
	v_lshlrev_b32_e32 v7, 8, v3
	v_lshl_add_u32 v7, v4, 4, v7
	global_load_dword v40, v7, s[8:9] offset:0
	global_load_dword v41, v7, s[8:9] offset:4
	global_load_dword v42, v7, s[8:9] offset:8
	global_load_dword v43, v7, s[8:9] offset:12
	global_load_dword v44, v7, s[8:9] offset:64
	global_load_dword v45, v7, s[8:9] offset:68
	global_load_dword v46, v7, s[8:9] offset:72
	global_load_dword v47, v7, s[8:9] offset:76
	global_load_dword v48, v7, s[8:9] offset:128
	global_load_dword v49, v7, s[8:9] offset:132
	global_load_dword v50, v7, s[8:9] offset:136
	global_load_dword v51, v7, s[8:9] offset:140
	global_load_dword v52, v7, s[8:9] offset:192
	global_load_dword v53, v7, s[8:9] offset:196
	global_load_dword v54, v7, s[8:9] offset:200
	global_load_dword v55, v7, s[8:9] offset:204
	global_load_dword v56, v7, s[10:11] offset:0
	global_load_dword v57, v7, s[10:11] offset:4
	global_load_dword v58, v7, s[10:11] offset:8
	global_load_dword v59, v7, s[10:11] offset:12
	global_load_dword v60, v7, s[10:11] offset:64
	global_load_dword v61, v7, s[10:11] offset:68
	global_load_dword v62, v7, s[10:11] offset:72
	global_load_dword v63, v7, s[10:11] offset:76
	global_load_dword v64, v7, s[10:11] offset:128
	global_load_dword v65, v7, s[10:11] offset:132
	global_load_dword v66, v7, s[10:11] offset:136
	global_load_dword v67, v7, s[10:11] offset:140
	global_load_dword v68, v7, s[10:11] offset:192
	global_load_dword v69, v7, s[10:11] offset:196
	global_load_dword v70, v7, s[10:11] offset:200
	global_load_dword v71, v7, s[10:11] offset:204
	s_lshl_b32 s6, s17, 6
	s_add_u32 s12, s66, s6
	s_addc_u32 s13, s67, 0
	v_lshlrev_b32_e32 v6, 2, v3
	global_load_dword v76, v6, s[12:13]
	s_mul_i32 s0, s18, 0x78000
	s_lshl_b32 s1, s17, 5
	s_add_i32 s0, s0, s1
	s_add_i32 s0, s0, 0xf911430
	s_add_u32 s22, s74, s0
	s_addc_u32 s23, s75, 0
	s_lshl_b32 s0, s17, 14
	s_add_i32 s0, s0, 0xa110000
	s_add_u32 s24, s74, s0
	s_addc_u32 s25, s75, 0
	s_lshl_b32 s0, s18, 17
	s_lshl_b32 s1, s17, 5
	s_add_i32 s0, s0, s1
	s_add_i32 s0, s0, 0xb910000
	s_add_u32 s26, s74, s0
	s_addc_u32 s27, s75, 0
	s_add_u32 s40, s22, 0x0
	s_addc_u32 s41, s23, 0
	s_add_u32 s42, s22, 0x1e000
	s_addc_u32 s43, s23, 0
	s_add_u32 s44, s22, 0x3c000
	s_addc_u32 s45, s23, 0
	s_add_u32 s46, s22, 0x5a000
	s_addc_u32 s47, s23, 0
	global_load_dwordx4 v[120:123], v83, s[40:41]
	global_load_dwordx4 v[124:127], v83, s[42:43]
	global_load_dwordx4 v[128:131], v83, s[44:45]
	global_load_dwordx4 v[132:135], v83, s[46:47]
	global_load_ushort v136, v84, s[40:41]
	global_load_ushort v137, v85, s[40:41]
	global_load_ushort v138, v86, s[40:41]
	global_load_ushort v139, v87, s[40:41]
	global_load_ushort v140, v84, s[42:43]
	global_load_ushort v141, v85, s[42:43]
	global_load_ushort v142, v86, s[42:43]
	global_load_ushort v143, v87, s[42:43]
	global_load_ushort v144, v84, s[44:45]
	global_load_ushort v145, v85, s[44:45]
	global_load_ushort v146, v86, s[44:45]
	global_load_ushort v147, v87, s[44:45]
	global_load_ushort v148, v84, s[46:47]
	global_load_ushort v149, v85, s[46:47]
	global_load_ushort v150, v86, s[46:47]
	global_load_ushort v151, v87, s[46:47]
	global_load_dwordx2 v[152:153], v199, s[24:25] offset:-4096
	global_load_dwordx2 v[154:155], v199, s[24:25]
	global_load_dwordx2 v[156:157], v204, s[24:25] offset:-4096
	global_load_dwordx2 v[158:159], v204, s[24:25]
	s_mov_b32 s19, 0
	s_mov_b32 s20, 0
	s_waitcnt vmcnt(0)
	v_xor_b32_e32 v56, 0x80000000, v56
	v_xor_b32_e32 v57, 0x80000000, v57
	v_xor_b32_e32 v58, 0x80000000, v58
	v_xor_b32_e32 v59, 0x80000000, v59
	v_xor_b32_e32 v60, 0x80000000, v60
	v_xor_b32_e32 v61, 0x80000000, v61
	v_xor_b32_e32 v62, 0x80000000, v62
	v_xor_b32_e32 v63, 0x80000000, v63
	v_xor_b32_e32 v64, 0x80000000, v64
	v_xor_b32_e32 v65, 0x80000000, v65
	v_xor_b32_e32 v66, 0x80000000, v66
	v_xor_b32_e32 v67, 0x80000000, v67
	v_xor_b32_e32 v68, 0x80000000, v68
	v_xor_b32_e32 v69, 0x80000000, v69
	v_xor_b32_e32 v70, 0x80000000, v70
	v_xor_b32_e32 v71, 0x80000000, v71
	ds_write_b64 v81, v[152:153] offset:0
	ds_write_b64 v81, v[154:155] offset:4096
	ds_write_b64 v81, v[156:157] offset:8192
	ds_write_b64 v81, v[158:159] offset:12288
	v_mov_b32_e32 v1, 1
	s_waitcnt lgkmcnt(0)
	ds_write_b32 v78, v1
	s_waitcnt lgkmcnt(0)
	s_barrier

; DI void s5_pass3_item(const Params& P, int bitem, unsigned char* smem) {
;     ...
;       const f32x2_t* e = (const f32x2_t*)(ws + WS_S5END) + (size_t)((b * 64 + grp) * 32) * 64 + lane;
;       f32x2_t ev[31];
; #pragma unroll
;       for (int j = 0; j < 31; ++j) ev[j] = e[(j < ch ? j : 0) * 64];
; #pragma unroll
;       for (int j = 0; j < 31; ++j) { const float ex = j < ch ? ev[j][0] : 0.f, ey = j < ch ? ev[j][1] : 0.f;
;           const float ncr = ab[2] * xr - ab[3] * xi + ex, nci = ab[2] * xi + ab[3] * xr + ey; xr = j < ch ? ncr : xr; xi = j < ch ? nci : xi; } }
;     ...
;         for (int tt = 0; tt < 16; ++tt) { const float bur = xs[lane * 17 + tt], bui = xs[(64 + lane) * 17 + tt];
;             const float nxr = ab[0] * xr - ab[1] * xi + bur, nxi = ab[0] * xi + ab[1] * xr + bui; xr = nxr; xi = nxi;
;             xs[lane * 17 + tt] = xr; xs[(64 + lane) * 17 + tt] = xi; }
.Ls5n_cloop:
	ds_read_b64 v[208:209], v1 offset:2048
	ds_read_b64 v[210:211], v1 offset:2560
	ds_read_b64 v[212:213], v1 offset:3072
	ds_read_b64 v[214:215], v1 offset:3584
	v_add_u32_e32 v1, 0x800, v1
	s_waitcnt lgkmcnt(7)
	v_fma_f32 v194, -v75, v193, v2
	v_fma_f32 v195, v75, v192, v3
	v_fma_f32 v192, v74, v192, v194
	v_fma_f32 v193, v74, v193, v195
	s_add_i32 s30, s30, 1
	s_cmp_ge_u32 s30, s18
	s_cbranch_scc1 .Ls5n_cdone
	s_waitcnt lgkmcnt(6)
	v_fma_f32 v194, -v75, v193, v4
	v_fma_f32 v195, v75, v192, v5
	v_fma_f32 v192, v74, v192, v194
	v_fma_f32 v193, v74, v193, v195
	s_add_i32 s30, s30, 1
	s_cmp_ge_u32 s30, s18
	s_cbranch_scc1 .Ls5n_cdone
	s_waitcnt lgkmcnt(5)
	v_fma_f32 v194, -v75, v193, v6
	v_fma_f32 v195, v75, v192, v7
	v_fma_f32 v192, v74, v192, v194
	v_fma_f32 v193, v74, v193, v195
	s_add_i32 s30, s30, 1
	s_cmp_ge_u32 s30, s18
	s_cbranch_scc1 .Ls5n_cdone
	s_waitcnt lgkmcnt(4)
	v_fma_f32 v194, -v75, v193, v246
	v_fma_f32 v195, v75, v192, v247
	v_fma_f32 v192, v74, v192, v194
	v_fma_f32 v193, v74, v193, v195
	s_add_i32 s30, s30, 1
	s_cmp_ge_u32 s30, s18
	s_cbranch_scc1 .Ls5n_cdone
	ds_read_b64 v[2:3], v1 offset:2048
	ds_read_b64 v[4:5], v1 offset:2560
	ds_read_b64 v[6:7], v1 offset:3072
	ds_read_b64 v[246:247], v1 offset:3584
	v_add_u32_e32 v1, 0x800, v1
	s_waitcnt lgkmcnt(7)
	v_fma_f32 v194, -v75, v193, v208
	v_fma_f32 v195, v75, v192, v209
	v_fma_f32 v192, v74, v192, v194
	v_fma_f32 v193, v74, v193, v195
	s_add_i32 s30, s30, 1
	s_cmp_ge_u32 s30, s18
	s_cbranch_scc1 .Ls5n_cdone
	s_waitcnt lgkmcnt(6)
	v_fma_f32 v194, -v75, v193, v210
	v_fma_f32 v195, v75, v192, v211
	v_fma_f32 v192, v74, v192, v194
	v_fma_f32 v193, v74, v193, v195
	s_add_i32 s30, s30, 1
	s_cmp_ge_u32 s30, s18
	s_cbranch_scc1 .Ls5n_cdone
	s_waitcnt lgkmcnt(5)
	v_fma_f32 v194, -v75, v193, v212
	v_fma_f32 v195, v75, v192, v213
	v_fma_f32 v192, v74, v192, v194
	v_fma_f32 v193, v74, v193, v195
	s_add_i32 s30, s30, 1
	s_cmp_ge_u32 s30, s18
	s_cbranch_scc1 .Ls5n_cdone
	s_waitcnt lgkmcnt(4)
	v_fma_f32 v194, -v75, v193, v214
	v_fma_f32 v195, v75, v192, v215
	v_fma_f32 v192, v74, v192, v194
	v_fma_f32 v193, v74, v193, v195
	s_add_i32 s30, s30, 1
	s_cmp_ge_u32 s30, s18
	s_cbranch_scc1 .Ls5n_cdone
	s_branch .Ls5n_cloop
.Ls5n_cdone:
	s_waitcnt lgkmcnt(0)
	s_mov_b64 s[28:29], s[26:27]
	v_mfma_f32_16x16x32_bf16 v[160:163], v[88:91], v[8:11], 0
	v_mfma_f32_16x16x32_bf16 v[164:167], v[88:91], v[12:15], 0
	v_mfma_f32_16x16x32_bf16 v[168:171], v[88:91], v[16:19], 0
	v_mfma_f32_16x16x32_bf16 v[172:175], v[88:91], v[20:23], 0
	v_mfma_f32_16x16x32_bf16 v[176:179], v[88:91], v[24:27], 0
	v_mfma_f32_16x16x32_bf16 v[180:183], v[88:91], v[28:31], 0
	v_mfma_f32_16x16x32_bf16 v[184:187], v[88:91], v[32:35], 0
	v_mfma_f32_16x16x32_bf16 v[188:191], v[88:91], v[36:39], 0
	s_nop 7
	v_permlane32_swap_b32_e32 v160, v168
	v_permlane32_swap_b32_e32 v161, v169
	v_permlane32_swap_b32_e32 v162, v170
	v_permlane32_swap_b32_e32 v163, v171
	v_permlane32_swap_b32_e32 v164, v172
	v_permlane32_swap_b32_e32 v165, v173
	v_permlane32_swap_b32_e32 v166, v174
	v_permlane32_swap_b32_e32 v167, v175
	v_permlane32_swap_b32_e32 v176, v184
	v_permlane32_swap_b32_e32 v177, v185
	v_permlane32_swap_b32_e32 v178, v186
	v_permlane32_swap_b32_e32 v179, v187
	v_permlane32_swap_b32_e32 v180, v188
	v_permlane32_swap_b32_e32 v181, v189
	v_permlane32_swap_b32_e32 v182, v190
	v_permlane32_swap_b32_e32 v183, v191
	v_permlane16_swap_b32_e32 v160, v164
	v_permlane16_swap_b32_e32 v161, v165
	v_permlane16_swap_b32_e32 v162, v166
	v_permlane16_swap_b32_e32 v163, v167
	v_permlane16_swap_b32_e32 v168, v172
	v_permlane16_swap_b32_e32 v169, v173
	v_permlane16_swap_b32_e32 v170, v174
	v_permlane16_swap_b32_e32 v171, v175
	v_permlane16_swap_b32_e32 v176, v180
	v_permlane16_swap_b32_e32 v177, v181
	v_permlane16_swap_b32_e32 v178, v182
	v_permlane16_swap_b32_e32 v179, v183
	v_permlane16_swap_b32_e32 v184, v188
	v_permlane16_swap_b32_e32 v185, v189
	v_permlane16_swap_b32_e32 v186, v190
	v_permlane16_swap_b32_e32 v187, v191
	v_fma_f32 v194, -v73, v193, v160
	v_fma_f32 v195, v73, v192, v176
	v_fma_f32 v160, v72, v192, v194
	v_fma_f32 v176, v72, v193, v195
	ds_write_addtid_b32 v160 offset:0
	ds_write_addtid_b32 v176 offset:256
	v_fma_f32 v194, -v73, v176, v161
	v_fma_f32 v195, v73, v160, v177
	v_fma_f32 v161, v72, v160, v194
	v_fma_f32 v177, v72, v176, v195
	ds_write_addtid_b32 v161 offset:528
	ds_write_addtid_b32 v177 offset:784
	v_fma_f32 v194, -v73, v177, v162
	v_fma_f32 v195, v73, v161, v178
	v_fma_f32 v162, v72, v161, v194
	v_fma_f32 v178, v72, v177, v195
	ds_write_addtid_b32 v162 offset:1056
	ds_write_addtid_b32 v178 offset:1312
	v_fma_f32 v194, -v73, v178, v163
	v_fma_f32 v195, v73, v162, v179
	v_fma_f32 v163, v72, v162, v194
	v_fma_f32 v179, v72, v178, v195
	ds_write_addtid_b32 v163 offset:1584
	ds_write_addtid_b32 v179 offset:1840
	v_fma_f32 v194, -v73, v179, v164
	v_fma_f32 v195, v73, v163, v180
	v_fma_f32 v164, v72, v163, v194
	v_fma_f32 v180, v72, v179, v195
	ds_write_addtid_b32 v164 offset:2112
	ds_write_addtid_b32 v180 offset:2368
	v_fma_f32 v194, -v73, v180, v165
	v_fma_f32 v195, v73, v164, v181
	v_fma_f32 v165, v72, v164, v194
	v_fma_f32 v181, v72, v180, v195
	ds_write_addtid_b32 v165 offset:2640
	ds_write_addtid_b32 v181 offset:2896
	v_fma_f32 v194, -v73, v181, v166
	v_fma_f32 v195, v73, v165, v182
	v_fma_f32 v166, v72, v165, v194
	v_fma_f32 v182, v72, v181, v195
	ds_write_addtid_b32 v166 offset:3168
	ds_write_addtid_b32 v182 offset:3424
	v_fma_f32 v194, -v73, v182, v167
	v_fma_f32 v195, v73, v166, v183
	v_fma_f32 v167, v72, v166, v194
	v_fma_f32 v183, v72, v182, v195
	ds_write_addtid_b32 v167 offset:3696
	ds_write_addtid_b32 v183 offset:3952
; DI void s5_pass3_item(const Params& P, int bitem, unsigned char* smem) {
;     ...
;         for (int tt = 0; tt < 16; ++tt) { const float bur = xs[lane * 17 + tt], bui = xs[(64 + lane) * 17 + tt];
;             const float nxr = ab[0] * xr - ab[1] * xi + bur, nxi = ab[0] * xi + ab[1] * xr + bui; xr = nxr; xi = nxi;
;             xs[lane * 17 + tt] = xr; xs[(64 + lane) * 17 + tt] = xi; }
;         asm volatile("s_waitcnt lgkmcnt(0)" ::: "memory");
;         f32x4 ya[4];
; #pragma unroll
;         for (int j = 0; j < 4; ++j) ya[j] = (f32x4){0.f, 0.f, 0.f, 0.f};
; #pragma unroll
;         for (int i = 0; i < 32; ++i) { const float a = xs[(4 * i + q) * 17 + r]; ya[i & 3] = __builtin_amdgcn_mfma_f32_16x16x4f32(a, cB[i], ya[i & 3], 0, 0, 0); }
	v_fma_f32 v194, -v73, v183, v168
	v_fma_f32 v195, v73, v167, v184
	v_fma_f32 v168, v72, v167, v194
	v_fma_f32 v184, v72, v183, v195
	ds_write_addtid_b32 v168 offset:4224
	ds_write_addtid_b32 v184 offset:4480
	v_fma_f32 v194, -v73, v184, v169
	v_fma_f32 v195, v73, v168, v185
	v_fma_f32 v169, v72, v168, v194
	v_fma_f32 v185, v72, v184, v195
	ds_write_addtid_b32 v169 offset:4752
	ds_write_addtid_b32 v185 offset:5008
	v_fma_f32 v194, -v73, v185, v170
	v_fma_f32 v195, v73, v169, v186
	v_fma_f32 v170, v72, v169, v194
	v_fma_f32 v186, v72, v185, v195
	ds_write_addtid_b32 v170 offset:5280
	ds_write_addtid_b32 v186 offset:5536
	v_fma_f32 v194, -v73, v186, v171
	v_fma_f32 v195, v73, v170, v187
	v_fma_f32 v171, v72, v170, v194
	v_fma_f32 v187, v72, v186, v195
	ds_write_addtid_b32 v171 offset:5808
	ds_write_addtid_b32 v187 offset:6064
	v_fma_f32 v194, -v73, v187, v172
	v_fma_f32 v195, v73, v171, v188
	v_fma_f32 v172, v72, v171, v194
	v_fma_f32 v188, v72, v187, v195
	ds_write_addtid_b32 v172 offset:6336
	ds_write_addtid_b32 v188 offset:6592
	v_fma_f32 v194, -v73, v188, v173
	v_fma_f32 v195, v73, v172, v189
	v_fma_f32 v173, v72, v172, v194
	v_fma_f32 v189, v72, v188, v195
	ds_write_addtid_b32 v173 offset:6864
	ds_write_addtid_b32 v189 offset:7120
	v_fma_f32 v194, -v73, v189, v174
	v_fma_f32 v195, v73, v173, v190
	v_fma_f32 v174, v72, v173, v194
	v_fma_f32 v190, v72, v189, v195
	ds_write_addtid_b32 v174 offset:7392
	ds_write_addtid_b32 v190 offset:7648
	v_fma_f32 v194, -v73, v190, v175
	v_fma_f32 v195, v73, v174, v191
	v_fma_f32 v175, v72, v174, v194
	v_fma_f32 v191, v72, v190, v195
	ds_write_addtid_b32 v175 offset:7920
	ds_write_addtid_b32 v191 offset:8176
	v_mov_b32_e32 v192, v175
	v_mov_b32_e32 v193, v191
	ds_read_b128 v[208:211], v77 offset:0
	ds_read_b128 v[212:215], v77 offset:64
	ds_read_b128 v[216:219], v77 offset:128
	ds_read_b128 v[220:223], v77 offset:192
	ds_read_b128 v[224:227], v77 offset:256
	ds_read_b128 v[228:231], v77 offset:320
	ds_read_b128 v[232:235], v77 offset:384
	ds_read_b128 v[236:239], v77 offset:448
	v_mfma_f32_16x16x32_bf16 v[160:163], v[92:95], v[8:11], 0
	v_mfma_f32_16x16x32_bf16 v[164:167], v[92:95], v[12:15], 0
	v_mfma_f32_16x16x32_bf16 v[168:171], v[92:95], v[16:19], 0
	v_mfma_f32_16x16x32_bf16 v[172:175], v[92:95], v[20:23], 0
	v_mfma_f32_16x16x32_bf16 v[176:179], v[92:95], v[24:27], 0
	v_mfma_f32_16x16x32_bf16 v[180:183], v[92:95], v[28:31], 0
	v_mfma_f32_16x16x32_bf16 v[184:187], v[92:95], v[32:35], 0
	v_mfma_f32_16x16x32_bf16 v[188:191], v[92:95], v[36:39], 0
	s_nop 7
	v_permlane32_swap_b32_e32 v160, v168
	v_permlane32_swap_b32_e32 v161, v169
	v_permlane32_swap_b32_e32 v162, v170
	v_permlane32_swap_b32_e32 v163, v171
	v_permlane32_swap_b32_e32 v164, v172
	v_permlane32_swap_b32_e32 v165, v173
	v_permlane32_swap_b32_e32 v166, v174
	v_permlane32_swap_b32_e32 v167, v175
	v_permlane32_swap_b32_e32 v176, v184
	v_permlane32_swap_b32_e32 v177, v185
	v_permlane32_swap_b32_e32 v178, v186
	v_permlane32_swap_b32_e32 v179, v187
	v_permlane32_swap_b32_e32 v180, v188
	v_permlane32_swap_b32_e32 v181, v189
	v_permlane32_swap_b32_e32 v182, v190
	v_permlane32_swap_b32_e32 v183, v191
	v_permlane16_swap_b32_e32 v160, v164
	v_permlane16_swap_b32_e32 v161, v165
	v_permlane16_swap_b32_e32 v162, v166
	v_permlane16_swap_b32_e32 v163, v167
	v_permlane16_swap_b32_e32 v168, v172
	v_permlane16_swap_b32_e32 v169, v173
	v_permlane16_swap_b32_e32 v170, v174
	v_permlane16_swap_b32_e32 v171, v175
	v_permlane16_swap_b32_e32 v176, v180
	v_permlane16_swap_b32_e32 v177, v181
	v_permlane16_swap_b32_e32 v178, v182
	v_permlane16_swap_b32_e32 v179, v183
	v_permlane16_swap_b32_e32 v184, v188
	v_permlane16_swap_b32_e32 v185, v189
	v_permlane16_swap_b32_e32 v186, v190
	v_permlane16_swap_b32_e32 v187, v191
	s_waitcnt lgkmcnt(7)
	v_mfma_f32_16x16x4_f32 v[200:203], v208, v40, 0
	v_mfma_f32_16x16x4_f32 v[240:243], v209, v41, 0
	v_mfma_f32_16x16x4_f32 v[200:203], v210, v42, v[200:203]
	v_mfma_f32_16x16x4_f32 v[240:243], v211, v43, v[240:243]
	s_waitcnt lgkmcnt(6)
	v_mfma_f32_16x16x4_f32 v[200:203], v212, v44, v[200:203]
	v_mfma_f32_16x16x4_f32 v[240:243], v213, v45, v[240:243]
	v_mfma_f32_16x16x4_f32 v[200:203], v214, v46, v[200:203]
	v_mfma_f32_16x16x4_f32 v[240:243], v215, v47, v[240:243]
	s_waitcnt lgkmcnt(5)
	v_mfma_f32_16x16x4_f32 v[200:203], v216, v48, v[200:203]
	v_mfma_f32_16x16x4_f32 v[240:243], v217, v49, v[240:243]
	v_mfma_f32_16x16x4_f32 v[200:203], v218, v50, v[200:203]
	v_mfma_f32_16x16x4_f32 v[240:243], v219, v51, v[240:243]
	s_waitcnt lgkmcnt(4)
	v_mfma_f32_16x16x4_f32 v[200:203], v220, v52, v[200:203]
	v_mfma_f32_16x16x4_f32 v[240:243], v221, v53, v[240:243]
	v_mfma_f32_16x16x4_f32 v[200:203], v222, v54, v[200:203]
	v_mfma_f32_16x16x4_f32 v[240:243], v223, v55, v[240:243]
	s_waitcnt lgkmcnt(3)
	v_mfma_f32_16x16x4_f32 v[200:203], v224, v56, v[200:203]
	v_mfma_f32_16x16x4_f32 v[240:243], v225, v57, v[240:243]
	v_mfma_f32_16x16x4_f32 v[200:203], v226, v58, v[200:203]
	v_mfma_f32_16x16x4_f32 v[240:243], v227, v59, v[240:243]
	s_waitcnt lgkmcnt(2)
	v_mfma_f32_16x16x4_f32 v[200:203], v228, v60, v[200:203]
	v_mfma_f32_16x16x4_f32 v[240:243], v229, v61, v[240:243]
	v_mfma_f32_16x16x4_f32 v[200:203], v230, v62, v[200:203]
	v_mfma_f32_16x16x4_f32 v[240:243], v231, v63, v[240:243]
	s_waitcnt lgkmcnt(1)
	v_mfma_f32_16x16x4_f32 v[200:203], v232, v64, v[200:203]
	v_mfma_f32_16x16x4_f32 v[240:243], v233, v65, v[240:243]
	v_mfma_f32_16x16x4_f32 v[200:203], v234, v66, v[200:203]
	v_mfma_f32_16x16x4_f32 v[240:243], v235, v67, v[240:243]
	s_waitcnt lgkmcnt(0)
; DI unsigned pk2(float a, float b) { f32x2_t v = {a, b}; return __builtin_bit_cast(unsigned, __builtin_convertvector(v, bf16x2_t)); }
; DI float gelu_tanh(float v) { const float z = 0.7978845608028654f * (v + 0.044715f * v * v * v); const float th = 1.0f - 2.0f * __builtin_amdgcn_rcpf(__builtin_amdgcn_exp2f(2.8853900817779268f * z) + 1.0f); return 0.5f * v * (1.0f + th); }
; DI void s5_pass3_item(const Params& P, int bitem, unsigned char* smem) {
;     ...
;         for (int tt = 0; tt < 16; ++tt) { const float bur = xs[lane * 17 + tt], bui = xs[(64 + lane) * 17 + tt];
;             const float nxr = ab[0] * xr - ab[1] * xi + bur, nxi = ab[0] * xi + ab[1] * xr + bui; xr = nxr; xi = nxi;
;             xs[lane * 17 + tt] = xr; xs[(64 + lane) * 17 + tt] = xi; }
;     ...
;         for (int i = 0; i < 32; ++i) { const float a = xs[(4 * i + q) * 17 + r]; ya[i & 3] = __builtin_amdgcn_mfma_f32_16x16x4f32(a, cB[i], ya[i & 3], 0, 0, 0); }
;         const f32x4 y = (ya[0] + ya[1]) + (ya[2] + ya[3]);
; #pragma unroll
;         for (int j = 0; j < 4; ++j) { const int tl = sub * 16 + 4 * q + j; const float v = y[j] + dsk * uv[j];
;             HG[(size_t)(b * TT + ch * 64 + tl) * 1024 + grp * 16 + r] = (bf16_t)(pk2(gelu_tanh(v), 0.f) & 0xffffu); }
	v_mfma_f32_16x16x4_f32 v[200:203], v236, v68, v[200:203]
	v_mfma_f32_16x16x4_f32 v[240:243], v237, v69, v[240:243]
	v_mfma_f32_16x16x4_f32 v[200:203], v238, v70, v[200:203]
	v_mfma_f32_16x16x4_f32 v[240:243], v239, v71, v[240:243]
	s_nop 9
	v_add_f32_e32 v1, v200, v240
	v_add_f32_e32 v2, v201, v241
	v_add_f32_e32 v3, v202, v242
	v_add_f32_e32 v4, v203, v243
	v_fmac_f32_e32 v1, v76, v104
	v_fmac_f32_e32 v2, v76, v105
	v_fmac_f32_e32 v3, v76, v106
	v_fmac_f32_e32 v4, v76, v107
	v_mul_f32_e32 v5, v1, v1
	v_mul_f32_e32 v6, v2, v2
	v_mul_f32_e32 v7, v3, v3
	v_mul_f32_e32 v246, v4, v4
	v_fma_f32 v5, v5, v80, v205
	v_fma_f32 v6, v6, v80, v205
	v_fma_f32 v7, v7, v80, v205
	v_fma_f32 v246, v246, v80, v205
	v_mul_f32_e32 v5, v5, v1
	v_mul_f32_e32 v6, v6, v2
	v_mul_f32_e32 v7, v7, v3
	v_mul_f32_e32 v246, v246, v4
	v_exp_f32_e32 v5, v5
	v_exp_f32_e32 v6, v6
	v_exp_f32_e32 v7, v7
	v_exp_f32_e32 v246, v246
	v_add_f32_e32 v5, 1.0, v5
	v_add_f32_e32 v6, 1.0, v6
	v_add_f32_e32 v7, 1.0, v7
	v_add_f32_e32 v246, 1.0, v246
	v_rcp_f32_e32 v5, v5
	v_rcp_f32_e32 v6, v6
	v_rcp_f32_e32 v7, v7
	v_rcp_f32_e32 v246, v246
	v_fma_f32 v1, -v1, v5, v1
	v_fma_f32 v2, -v2, v6, v2
	v_fma_f32 v3, -v3, v7, v3
	v_fma_f32 v4, -v4, v246, v4
	v_cvt_pk_bf16_f32 v1, v1, v1
	v_cvt_pk_bf16_f32 v2, v2, v2
	v_cvt_pk_bf16_f32 v3, v3, v3
	v_cvt_pk_bf16_f32 v4, v4, v4
	global_store_short v198, v1, s[28:29] offset:-4096
	global_store_short v198, v2, s[28:29] offset:-2048
	global_store_short v198, v3, s[28:29] offset:0
	global_store_short v198, v4, s[28:29] offset:2048
	s_add_u32 s28, s28, 0x8000
	s_addc_u32 s29, s29, 0
	v_fma_f32 v194, -v73, v193, v160
	v_fma_f32 v195, v73, v192, v176
	v_fma_f32 v160, v72, v192, v194
	v_fma_f32 v176, v72, v193, v195
	ds_write_addtid_b32 v160 offset:0
	ds_write_addtid_b32 v176 offset:256
	v_fma_f32 v194, -v73, v176, v161
	v_fma_f32 v195, v73, v160, v177
	v_fma_f32 v161, v72, v160, v194
	v_fma_f32 v177, v72, v176, v195
	ds_write_addtid_b32 v161 offset:528
	ds_write_addtid_b32 v177 offset:784
	v_fma_f32 v194, -v73, v177, v162
	v_fma_f32 v195, v73, v161, v178
	v_fma_f32 v162, v72, v161, v194
	v_fma_f32 v178, v72, v177, v195
	ds_write_addtid_b32 v162 offset:1056
	ds_write_addtid_b32 v178 offset:1312
	v_fma_f32 v194, -v73, v178, v163
	v_fma_f32 v195, v73, v162, v179
	v_fma_f32 v163, v72, v162, v194
	v_fma_f32 v179, v72, v178, v195
	ds_write_addtid_b32 v163 offset:1584
	ds_write_addtid_b32 v179 offset:1840
	v_fma_f32 v194, -v73, v179, v164
	v_fma_f32 v195, v73, v163, v180
	v_fma_f32 v164, v72, v163, v194
	v_fma_f32 v180, v72, v179, v195
	ds_write_addtid_b32 v164 offset:2112
	ds_write_addtid_b32 v180 offset:2368
	v_fma_f32 v194, -v73, v180, v165
	v_fma_f32 v195, v73, v164, v181
	v_fma_f32 v165, v72, v164, v194
	v_fma_f32 v181, v72, v180, v195
	ds_write_addtid_b32 v165 offset:2640
	ds_write_addtid_b32 v181 offset:2896
	v_fma_f32 v194, -v73, v181, v166
	v_fma_f32 v195, v73, v165, v182
	v_fma_f32 v166, v72, v165, v194
	v_fma_f32 v182, v72, v181, v195
	ds_write_addtid_b32 v166 offset:3168
	ds_write_addtid_b32 v182 offset:3424
	v_fma_f32 v194, -v73, v182, v167
	v_fma_f32 v195, v73, v166, v183
	v_fma_f32 v167, v72, v166, v194
	v_fma_f32 v183, v72, v182, v195
	ds_write_addtid_b32 v167 offset:3696
	ds_write_addtid_b32 v183 offset:3952
	v_fma_f32 v194, -v73, v183, v168
	v_fma_f32 v195, v73, v167, v184
	v_fma_f32 v168, v72, v167, v194
	v_fma_f32 v184, v72, v183, v195
	ds_write_addtid_b32 v168 offset:4224
	ds_write_addtid_b32 v184 offset:4480
	v_fma_f32 v194, -v73, v184, v169
	v_fma_f32 v195, v73, v168, v185
	v_fma_f32 v169, v72, v168, v194
	v_fma_f32 v185, v72, v184, v195
	ds_write_addtid_b32 v169 offset:4752
	ds_write_addtid_b32 v185 offset:5008
	v_fma_f32 v194, -v73, v185, v170
	v_fma_f32 v195, v73, v169, v186
	v_fma_f32 v170, v72, v169, v194
	v_fma_f32 v186, v72, v185, v195
	ds_write_addtid_b32 v170 offset:5280
	ds_write_addtid_b32 v186 offset:5536
	v_fma_f32 v194, -v73, v186, v171
	v_fma_f32 v195, v73, v170, v187
	v_fma_f32 v171, v72, v170, v194
	v_fma_f32 v187, v72, v186, v195
	ds_write_addtid_b32 v171 offset:5808
	ds_write_addtid_b32 v187 offset:6064
	v_fma_f32 v194, -v73, v187, v172
	v_fma_f32 v195, v73, v171, v188
	v_fma_f32 v172, v72, v171, v194
	v_fma_f32 v188, v72, v187, v195
	ds_write_addtid_b32 v172 offset:6336
	ds_write_addtid_b32 v188 offset:6592
	v_fma_f32 v194, -v73, v188, v173
	v_fma_f32 v195, v73, v172, v189
	v_fma_f32 v173, v72, v172, v194
	v_fma_f32 v189, v72, v188, v195
	ds_write_addtid_b32 v173 offset:6864
	ds_write_addtid_b32 v189 offset:7120
	v_fma_f32 v194, -v73, v189, v174
	v_fma_f32 v195, v73, v173, v190
	v_fma_f32 v174, v72, v173, v194
	v_fma_f32 v190, v72, v189, v195
	ds_write_addtid_b32 v174 offset:7392
	ds_write_addtid_b32 v190 offset:7648
	v_fma_f32 v194, -v73, v190, v175
	v_fma_f32 v195, v73, v174, v191
	v_fma_f32 v175, v72, v174, v194
	v_fma_f32 v191, v72, v190, v195
	ds_write_addtid_b32 v175 offset:7920
	ds_write_addtid_b32 v191 offset:8176
	v_mov_b32_e32 v192, v175
	v_mov_b32_e32 v193, v191
	ds_read_b128 v[208:211], v77 offset:0
	ds_read_b128 v[212:215], v77 offset:64
	ds_read_b128 v[216:219], v77 offset:128
	ds_read_b128 v[220:223], v77 offset:192
	ds_read_b128 v[224:227], v77 offset:256
	ds_read_b128 v[228:231], v77 offset:320
	ds_read_b128 v[232:235], v77 offset:384
	ds_read_b128 v[236:239], v77 offset:448
	v_mfma_f32_16x16x32_bf16 v[160:163], v[96:99], v[8:11], 0
	v_mfma_f32_16x16x32_bf16 v[164:167], v[96:99], v[12:15], 0
	v_mfma_f32_16x16x32_bf16 v[168:171], v[96:99], v[16:19], 0
	v_mfma_f32_16x16x32_bf16 v[172:175], v[96:99], v[20:23], 0
	v_mfma_f32_16x16x32_bf16 v[176:179], v[96:99], v[24:27], 0
	v_mfma_f32_16x16x32_bf16 v[180:183], v[96:99], v[28:31], 0
	v_mfma_f32_16x16x32_bf16 v[184:187], v[96:99], v[32:35], 0
	v_mfma_f32_16x16x32_bf16 v[188:191], v[96:99], v[36:39], 0
	s_nop 7
	v_permlane32_swap_b32_e32 v160, v168
	v_permlane32_swap_b32_e32 v161, v169
	v_permlane32_swap_b32_e32 v162, v170
	v_permlane32_swap_b32_e32 v163, v171
	v_permlane32_swap_b32_e32 v164, v172
	v_permlane32_swap_b32_e32 v165, v173
	v_permlane32_swap_b32_e32 v166, v174
	v_permlane32_swap_b32_e32 v167, v175
	v_permlane32_swap_b32_e32 v176, v184
	v_permlane32_swap_b32_e32 v177, v185
	v_permlane32_swap_b32_e32 v178, v186
	v_permlane32_swap_b32_e32 v179, v187
	v_permlane32_swap_b32_e32 v180, v188
	v_permlane32_swap_b32_e32 v181, v189
	v_permlane32_swap_b32_e32 v182, v190
	v_permlane32_swap_b32_e32 v183, v191
	v_permlane16_swap_b32_e32 v160, v164
	v_permlane16_swap_b32_e32 v161, v165
	v_permlane16_swap_b32_e32 v162, v166
	v_permlane16_swap_b32_e32 v163, v167
	v_permlane16_swap_b32_e32 v168, v172
	v_permlane16_swap_b32_e32 v169, v173
	v_permlane16_swap_b32_e32 v170, v174
	v_permlane16_swap_b32_e32 v171, v175
	v_permlane16_swap_b32_e32 v176, v180
	v_permlane16_swap_b32_e32 v177, v181
	v_permlane16_swap_b32_e32 v178, v182
	v_permlane16_swap_b32_e32 v179, v183
	v_permlane16_swap_b32_e32 v184, v188
	v_permlane16_swap_b32_e32 v185, v189
	v_permlane16_swap_b32_e32 v186, v190
	v_permlane16_swap_b32_e32 v187, v191
	s_waitcnt lgkmcnt(7)
; DI unsigned pk2(float a, float b) { f32x2_t v = {a, b}; return __builtin_bit_cast(unsigned, __builtin_convertvector(v, bf16x2_t)); }
; DI float gelu_tanh(float v) { const float z = 0.7978845608028654f * (v + 0.044715f * v * v * v); const float th = 1.0f - 2.0f * __builtin_amdgcn_rcpf(__builtin_amdgcn_exp2f(2.8853900817779268f * z) + 1.0f); return 0.5f * v * (1.0f + th); }
; DI void s5_pass3_item(const Params& P, int bitem, unsigned char* smem) {
;     ...
;         for (int tt = 0; tt < 16; ++tt) { const float bur = xs[lane * 17 + tt], bui = xs[(64 + lane) * 17 + tt];
;             const float nxr = ab[0] * xr - ab[1] * xi + bur, nxi = ab[0] * xi + ab[1] * xr + bui; xr = nxr; xi = nxi;
;             xs[lane * 17 + tt] = xr; xs[(64 + lane) * 17 + tt] = xi; }
;         asm volatile("s_waitcnt lgkmcnt(0)" ::: "memory");
;         f32x4 ya[4];
; #pragma unroll
;         for (int j = 0; j < 4; ++j) ya[j] = (f32x4){0.f, 0.f, 0.f, 0.f};
; #pragma unroll
;         for (int i = 0; i < 32; ++i) { const float a = xs[(4 * i + q) * 17 + r]; ya[i & 3] = __builtin_amdgcn_mfma_f32_16x16x4f32(a, cB[i], ya[i & 3], 0, 0, 0); }
;         const f32x4 y = (ya[0] + ya[1]) + (ya[2] + ya[3]);
; #pragma unroll
;         for (int j = 0; j < 4; ++j) { const int tl = sub * 16 + 4 * q + j; const float v = y[j] + dsk * uv[j];
;             HG[(size_t)(b * TT + ch * 64 + tl) * 1024 + grp * 16 + r] = (bf16_t)(pk2(gelu_tanh(v), 0.f) & 0xffffu); }
	v_mfma_f32_16x16x4_f32 v[200:203], v208, v40, 0
	v_mfma_f32_16x16x4_f32 v[240:243], v209, v41, 0
	v_mfma_f32_16x16x4_f32 v[200:203], v210, v42, v[200:203]
	v_mfma_f32_16x16x4_f32 v[240:243], v211, v43, v[240:243]
	s_waitcnt lgkmcnt(6)
	v_mfma_f32_16x16x4_f32 v[200:203], v212, v44, v[200:203]
	v_mfma_f32_16x16x4_f32 v[240:243], v213, v45, v[240:243]
	v_mfma_f32_16x16x4_f32 v[200:203], v214, v46, v[200:203]
	v_mfma_f32_16x16x4_f32 v[240:243], v215, v47, v[240:243]
	s_waitcnt lgkmcnt(5)
	v_mfma_f32_16x16x4_f32 v[200:203], v216, v48, v[200:203]
	v_mfma_f32_16x16x4_f32 v[240:243], v217, v49, v[240:243]
	v_mfma_f32_16x16x4_f32 v[200:203], v218, v50, v[200:203]
	v_mfma_f32_16x16x4_f32 v[240:243], v219, v51, v[240:243]
	s_waitcnt lgkmcnt(4)
	v_mfma_f32_16x16x4_f32 v[200:203], v220, v52, v[200:203]
	v_mfma_f32_16x16x4_f32 v[240:243], v221, v53, v[240:243]
	v_mfma_f32_16x16x4_f32 v[200:203], v222, v54, v[200:203]
	v_mfma_f32_16x16x4_f32 v[240:243], v223, v55, v[240:243]
	s_waitcnt lgkmcnt(3)
	v_mfma_f32_16x16x4_f32 v[200:203], v224, v56, v[200:203]
	v_mfma_f32_16x16x4_f32 v[240:243], v225, v57, v[240:243]
	v_mfma_f32_16x16x4_f32 v[200:203], v226, v58, v[200:203]
	v_mfma_f32_16x16x4_f32 v[240:243], v227, v59, v[240:243]
	s_waitcnt lgkmcnt(2)
	v_mfma_f32_16x16x4_f32 v[200:203], v228, v60, v[200:203]
	v_mfma_f32_16x16x4_f32 v[240:243], v229, v61, v[240:243]
	v_mfma_f32_16x16x4_f32 v[200:203], v230, v62, v[200:203]
	v_mfma_f32_16x16x4_f32 v[240:243], v231, v63, v[240:243]
	s_waitcnt lgkmcnt(1)
	v_mfma_f32_16x16x4_f32 v[200:203], v232, v64, v[200:203]
	v_mfma_f32_16x16x4_f32 v[240:243], v233, v65, v[240:243]
	v_mfma_f32_16x16x4_f32 v[200:203], v234, v66, v[200:203]
	v_mfma_f32_16x16x4_f32 v[240:243], v235, v67, v[240:243]
	s_waitcnt lgkmcnt(0)
	v_mfma_f32_16x16x4_f32 v[200:203], v236, v68, v[200:203]
	v_mfma_f32_16x16x4_f32 v[240:243], v237, v69, v[240:243]
	v_mfma_f32_16x16x4_f32 v[200:203], v238, v70, v[200:203]
	v_mfma_f32_16x16x4_f32 v[240:243], v239, v71, v[240:243]
	s_nop 9
	v_add_f32_e32 v1, v200, v240
	v_add_f32_e32 v2, v201, v241
	v_add_f32_e32 v3, v202, v242
	v_add_f32_e32 v4, v203, v243
	v_fmac_f32_e32 v1, v76, v108
	v_fmac_f32_e32 v2, v76, v109
	v_fmac_f32_e32 v3, v76, v110
	v_fmac_f32_e32 v4, v76, v111
	v_mul_f32_e32 v5, v1, v1
	v_mul_f32_e32 v6, v2, v2
	v_mul_f32_e32 v7, v3, v3
	v_mul_f32_e32 v246, v4, v4
	v_fma_f32 v5, v5, v80, v205
	v_fma_f32 v6, v6, v80, v205
	v_fma_f32 v7, v7, v80, v205
	v_fma_f32 v246, v246, v80, v205
	v_mul_f32_e32 v5, v5, v1
	v_mul_f32_e32 v6, v6, v2
	v_mul_f32_e32 v7, v7, v3
	v_mul_f32_e32 v246, v246, v4
	v_exp_f32_e32 v5, v5
	v_exp_f32_e32 v6, v6
	v_exp_f32_e32 v7, v7
	v_exp_f32_e32 v246, v246
	v_add_f32_e32 v5, 1.0, v5
	v_add_f32_e32 v6, 1.0, v6
	v_add_f32_e32 v7, 1.0, v7
	v_add_f32_e32 v246, 1.0, v246
	v_rcp_f32_e32 v5, v5
	v_rcp_f32_e32 v6, v6
	v_rcp_f32_e32 v7, v7
	v_rcp_f32_e32 v246, v246
	v_fma_f32 v1, -v1, v5, v1
	v_fma_f32 v2, -v2, v6, v2
	v_fma_f32 v3, -v3, v7, v3
	v_fma_f32 v4, -v4, v246, v4
	v_cvt_pk_bf16_f32 v1, v1, v1
	v_cvt_pk_bf16_f32 v2, v2, v2
	v_cvt_pk_bf16_f32 v3, v3, v3
	v_cvt_pk_bf16_f32 v4, v4, v4
	global_store_short v198, v1, s[28:29] offset:-4096
	global_store_short v198, v2, s[28:29] offset:-2048
	global_store_short v198, v3, s[28:29] offset:0
	global_store_short v198, v4, s[28:29] offset:2048
	s_add_u32 s28, s28, 0x8000
	s_addc_u32 s29, s29, 0
	s_cmp_eq_u32 s19, 7
	s_cbranch_scc1 .Ls5n_nostage
	s_waitcnt vmcnt(8)
	s_xor_b32 s0, s20, 0x4000
	v_add_u32_e32 v1, s0, v81
	ds_write_b64 v1, v[152:153] offset:0
	ds_write_b64 v1, v[154:155] offset:4096
	ds_write_b64 v1, v[156:157] offset:8192
	ds_write_b64 v1, v[158:159] offset:12288
	s_add_i32 s0, s19, 2
	v_mov_b32_e32 v2, s0
	s_waitcnt lgkmcnt(0)
	ds_write_b32 v78, v2
.Ls5n_nostage:
	v_fma_f32 v194, -v73, v193, v160
	v_fma_f32 v195, v73, v192, v176
	v_fma_f32 v160, v72, v192, v194
	v_fma_f32 v176, v72, v193, v195
	ds_write_addtid_b32 v160 offset:0
	ds_write_addtid_b32 v176 offset:256
	v_fma_f32 v194, -v73, v176, v161
	v_fma_f32 v195, v73, v160, v177
	v_fma_f32 v161, v72, v160, v194
	v_fma_f32 v177, v72, v176, v195
	ds_write_addtid_b32 v161 offset:528
	ds_write_addtid_b32 v177 offset:784
	v_fma_f32 v194, -v73, v177, v162
	v_fma_f32 v195, v73, v161, v178
	v_fma_f32 v162, v72, v161, v194
	v_fma_f32 v178, v72, v177, v195
	ds_write_addtid_b32 v162 offset:1056
	ds_write_addtid_b32 v178 offset:1312
	v_fma_f32 v194, -v73, v178, v163
	v_fma_f32 v195, v73, v162, v179
	v_fma_f32 v163, v72, v162, v194
	v_fma_f32 v179, v72, v178, v195
	ds_write_addtid_b32 v163 offset:1584
	ds_write_addtid_b32 v179 offset:1840
	v_fma_f32 v194, -v73, v179, v164
	v_fma_f32 v195, v73, v163, v180
	v_fma_f32 v164, v72, v163, v194
	v_fma_f32 v180, v72, v179, v195
	ds_write_addtid_b32 v164 offset:2112
	ds_write_addtid_b32 v180 offset:2368
	v_fma_f32 v194, -v73, v180, v165
	v_fma_f32 v195, v73, v164, v181
	v_fma_f32 v165, v72, v164, v194
	v_fma_f32 v181, v72, v180, v195
	ds_write_addtid_b32 v165 offset:2640
	ds_write_addtid_b32 v181 offset:2896
	v_fma_f32 v194, -v73, v181, v166
	v_fma_f32 v195, v73, v165, v182
	v_fma_f32 v166, v72, v165, v194
	v_fma_f32 v182, v72, v181, v195
	ds_write_addtid_b32 v166 offset:3168
	ds_write_addtid_b32 v182 offset:3424
	v_fma_f32 v194, -v73, v182, v167
	v_fma_f32 v195, v73, v166, v183
	v_fma_f32 v167, v72, v166, v194
	v_fma_f32 v183, v72, v182, v195
	ds_write_addtid_b32 v167 offset:3696
	ds_write_addtid_b32 v183 offset:3952
	v_fma_f32 v194, -v73, v183, v168
	v_fma_f32 v195, v73, v167, v184
	v_fma_f32 v168, v72, v167, v194
	v_fma_f32 v184, v72, v183, v195
	ds_write_addtid_b32 v168 offset:4224
	ds_write_addtid_b32 v184 offset:4480
	v_fma_f32 v194, -v73, v184, v169
; DI void s5_pass3_item(const Params& P, int bitem, unsigned char* smem) {
;     ...
;         for (int tt = 0; tt < 16; ++tt) { const float bur = xs[lane * 17 + tt], bui = xs[(64 + lane) * 17 + tt];
;             const float nxr = ab[0] * xr - ab[1] * xi + bur, nxi = ab[0] * xi + ab[1] * xr + bui; xr = nxr; xi = nxi;
;             xs[lane * 17 + tt] = xr; xs[(64 + lane) * 17 + tt] = xi; }
;         asm volatile("s_waitcnt lgkmcnt(0)" ::: "memory");
;         f32x4 ya[4];
; #pragma unroll
;         for (int j = 0; j < 4; ++j) ya[j] = (f32x4){0.f, 0.f, 0.f, 0.f};
; #pragma unroll
;         for (int i = 0; i < 32; ++i) { const float a = xs[(4 * i + q) * 17 + r]; ya[i & 3] = __builtin_amdgcn_mfma_f32_16x16x4f32(a, cB[i], ya[i & 3], 0, 0, 0); }
	v_fma_f32 v195, v73, v168, v185
	v_fma_f32 v169, v72, v168, v194
	v_fma_f32 v185, v72, v184, v195
	ds_write_addtid_b32 v169 offset:4752
	ds_write_addtid_b32 v185 offset:5008
	v_fma_f32 v194, -v73, v185, v170
	v_fma_f32 v195, v73, v169, v186
	v_fma_f32 v170, v72, v169, v194
	v_fma_f32 v186, v72, v185, v195
	ds_write_addtid_b32 v170 offset:5280
	ds_write_addtid_b32 v186 offset:5536
	v_fma_f32 v194, -v73, v186, v171
	v_fma_f32 v195, v73, v170, v187
	v_fma_f32 v171, v72, v170, v194
	v_fma_f32 v187, v72, v186, v195
	ds_write_addtid_b32 v171 offset:5808
	ds_write_addtid_b32 v187 offset:6064
	v_fma_f32 v194, -v73, v187, v172
	v_fma_f32 v195, v73, v171, v188
	v_fma_f32 v172, v72, v171, v194
	v_fma_f32 v188, v72, v187, v195
	ds_write_addtid_b32 v172 offset:6336
	ds_write_addtid_b32 v188 offset:6592
	v_fma_f32 v194, -v73, v188, v173
	v_fma_f32 v195, v73, v172, v189
	v_fma_f32 v173, v72, v172, v194
	v_fma_f32 v189, v72, v188, v195
	ds_write_addtid_b32 v173 offset:6864
	ds_write_addtid_b32 v189 offset:7120
	v_fma_f32 v194, -v73, v189, v174
	v_fma_f32 v195, v73, v173, v190
	v_fma_f32 v174, v72, v173, v194
	v_fma_f32 v190, v72, v189, v195
	ds_write_addtid_b32 v174 offset:7392
	ds_write_addtid_b32 v190 offset:7648
	v_fma_f32 v194, -v73, v190, v175
	v_fma_f32 v195, v73, v174, v191
	v_fma_f32 v175, v72, v174, v194
	v_fma_f32 v191, v72, v190, v195
	ds_write_addtid_b32 v175 offset:7920
	ds_write_addtid_b32 v191 offset:8176
	v_mov_b32_e32 v192, v175
	v_mov_b32_e32 v193, v191
	ds_read_b128 v[208:211], v77 offset:0
	ds_read_b128 v[212:215], v77 offset:64
	ds_read_b128 v[216:219], v77 offset:128
	ds_read_b128 v[220:223], v77 offset:192
	ds_read_b128 v[224:227], v77 offset:256
	ds_read_b128 v[228:231], v77 offset:320
	ds_read_b128 v[232:235], v77 offset:384
	ds_read_b128 v[236:239], v77 offset:448
	v_mfma_f32_16x16x32_bf16 v[160:163], v[100:103], v[8:11], 0
	v_mfma_f32_16x16x32_bf16 v[164:167], v[100:103], v[12:15], 0
	v_mfma_f32_16x16x32_bf16 v[168:171], v[100:103], v[16:19], 0
	v_mfma_f32_16x16x32_bf16 v[172:175], v[100:103], v[20:23], 0
	v_mfma_f32_16x16x32_bf16 v[176:179], v[100:103], v[24:27], 0
	v_mfma_f32_16x16x32_bf16 v[180:183], v[100:103], v[28:31], 0
	v_mfma_f32_16x16x32_bf16 v[184:187], v[100:103], v[32:35], 0
	v_mfma_f32_16x16x32_bf16 v[188:191], v[100:103], v[36:39], 0
	s_nop 7
	v_permlane32_swap_b32_e32 v160, v168
	v_permlane32_swap_b32_e32 v161, v169
	v_permlane32_swap_b32_e32 v162, v170
	v_permlane32_swap_b32_e32 v163, v171
	v_permlane32_swap_b32_e32 v164, v172
	v_permlane32_swap_b32_e32 v165, v173
	v_permlane32_swap_b32_e32 v166, v174
	v_permlane32_swap_b32_e32 v167, v175
	v_permlane32_swap_b32_e32 v176, v184
	v_permlane32_swap_b32_e32 v177, v185
	v_permlane32_swap_b32_e32 v178, v186
	v_permlane32_swap_b32_e32 v179, v187
	v_permlane32_swap_b32_e32 v180, v188
	v_permlane32_swap_b32_e32 v181, v189
	v_permlane32_swap_b32_e32 v182, v190
	v_permlane32_swap_b32_e32 v183, v191
	v_permlane16_swap_b32_e32 v160, v164
	v_permlane16_swap_b32_e32 v161, v165
	v_permlane16_swap_b32_e32 v162, v166
	v_permlane16_swap_b32_e32 v163, v167
	v_permlane16_swap_b32_e32 v168, v172
	v_permlane16_swap_b32_e32 v169, v173
	v_permlane16_swap_b32_e32 v170, v174
	v_permlane16_swap_b32_e32 v171, v175
	v_permlane16_swap_b32_e32 v176, v180
	v_permlane16_swap_b32_e32 v177, v181
	v_permlane16_swap_b32_e32 v178, v182
	v_permlane16_swap_b32_e32 v179, v183
	v_permlane16_swap_b32_e32 v184, v188
	v_permlane16_swap_b32_e32 v185, v189
	v_permlane16_swap_b32_e32 v186, v190
	v_permlane16_swap_b32_e32 v187, v191
	s_waitcnt lgkmcnt(7)
	v_mfma_f32_16x16x4_f32 v[200:203], v208, v40, 0
	v_mfma_f32_16x16x4_f32 v[240:243], v209, v41, 0
	v_mfma_f32_16x16x4_f32 v[200:203], v210, v42, v[200:203]
	v_mfma_f32_16x16x4_f32 v[240:243], v211, v43, v[240:243]
	s_waitcnt lgkmcnt(6)
	v_mfma_f32_16x16x4_f32 v[200:203], v212, v44, v[200:203]
	v_mfma_f32_16x16x4_f32 v[240:243], v213, v45, v[240:243]
	v_mfma_f32_16x16x4_f32 v[200:203], v214, v46, v[200:203]
	v_mfma_f32_16x16x4_f32 v[240:243], v215, v47, v[240:243]
	s_waitcnt lgkmcnt(5)
	v_mfma_f32_16x16x4_f32 v[200:203], v216, v48, v[200:203]
	v_mfma_f32_16x16x4_f32 v[240:243], v217, v49, v[240:243]
	v_mfma_f32_16x16x4_f32 v[200:203], v218, v50, v[200:203]
	v_mfma_f32_16x16x4_f32 v[240:243], v219, v51, v[240:243]
	s_waitcnt lgkmcnt(4)
	v_mfma_f32_16x16x4_f32 v[200:203], v220, v52, v[200:203]
	v_mfma_f32_16x16x4_f32 v[240:243], v221, v53, v[240:243]
	v_mfma_f32_16x16x4_f32 v[200:203], v222, v54, v[200:203]
	v_mfma_f32_16x16x4_f32 v[240:243], v223, v55, v[240:243]
	s_waitcnt lgkmcnt(3)
	v_mfma_f32_16x16x4_f32 v[200:203], v224, v56, v[200:203]
	v_mfma_f32_16x16x4_f32 v[240:243], v225, v57, v[240:243]
	v_mfma_f32_16x16x4_f32 v[200:203], v226, v58, v[200:203]
	v_mfma_f32_16x16x4_f32 v[240:243], v227, v59, v[240:243]
	s_waitcnt lgkmcnt(2)
	v_mfma_f32_16x16x4_f32 v[200:203], v228, v60, v[200:203]
	v_mfma_f32_16x16x4_f32 v[240:243], v229, v61, v[240:243]
	v_mfma_f32_16x16x4_f32 v[200:203], v230, v62, v[200:203]
	v_mfma_f32_16x16x4_f32 v[240:243], v231, v63, v[240:243]
	s_waitcnt lgkmcnt(1)
	v_mfma_f32_16x16x4_f32 v[200:203], v232, v64, v[200:203]
	v_mfma_f32_16x16x4_f32 v[240:243], v233, v65, v[240:243]
	v_mfma_f32_16x16x4_f32 v[200:203], v234, v66, v[200:203]
	v_mfma_f32_16x16x4_f32 v[240:243], v235, v67, v[240:243]
	s_waitcnt lgkmcnt(0)
; DI unsigned pk2(float a, float b) { f32x2_t v = {a, b}; return __builtin_bit_cast(unsigned, __builtin_convertvector(v, bf16x2_t)); }
; DI float gelu_tanh(float v) { const float z = 0.7978845608028654f * (v + 0.044715f * v * v * v); const float th = 1.0f - 2.0f * __builtin_amdgcn_rcpf(__builtin_amdgcn_exp2f(2.8853900817779268f * z) + 1.0f); return 0.5f * v * (1.0f + th); }
; DI void s5_pass3_item(const Params& P, int bitem, unsigned char* smem) {
;     ...
;         for (int tt = 0; tt < 16; ++tt) { const float bur = xs[lane * 17 + tt], bui = xs[(64 + lane) * 17 + tt];
;             const float nxr = ab[0] * xr - ab[1] * xi + bur, nxi = ab[0] * xi + ab[1] * xr + bui; xr = nxr; xi = nxi;
;             xs[lane * 17 + tt] = xr; xs[(64 + lane) * 17 + tt] = xi; }
;     ...
;         for (int i = 0; i < 32; ++i) { const float a = xs[(4 * i + q) * 17 + r]; ya[i & 3] = __builtin_amdgcn_mfma_f32_16x16x4f32(a, cB[i], ya[i & 3], 0, 0, 0); }
;         const f32x4 y = (ya[0] + ya[1]) + (ya[2] + ya[3]);
; #pragma unroll
;         for (int j = 0; j < 4; ++j) { const int tl = sub * 16 + 4 * q + j; const float v = y[j] + dsk * uv[j];
;             HG[(size_t)(b * TT + ch * 64 + tl) * 1024 + grp * 16 + r] = (bf16_t)(pk2(gelu_tanh(v), 0.f) & 0xffffu); }
	v_mfma_f32_16x16x4_f32 v[200:203], v236, v68, v[200:203]
	v_mfma_f32_16x16x4_f32 v[240:243], v237, v69, v[240:243]
	v_mfma_f32_16x16x4_f32 v[200:203], v238, v70, v[200:203]
	v_mfma_f32_16x16x4_f32 v[240:243], v239, v71, v[240:243]
	s_nop 9
	v_add_f32_e32 v1, v200, v240
	v_add_f32_e32 v2, v201, v241
	v_add_f32_e32 v3, v202, v242
	v_add_f32_e32 v4, v203, v243
	v_fmac_f32_e32 v1, v76, v112
	v_fmac_f32_e32 v2, v76, v113
	v_fmac_f32_e32 v3, v76, v114
	v_fmac_f32_e32 v4, v76, v115
	v_mul_f32_e32 v5, v1, v1
	v_mul_f32_e32 v6, v2, v2
	v_mul_f32_e32 v7, v3, v3
	v_mul_f32_e32 v246, v4, v4
	v_fma_f32 v5, v5, v80, v205
	v_fma_f32 v6, v6, v80, v205
	v_fma_f32 v7, v7, v80, v205
	v_fma_f32 v246, v246, v80, v205
	v_mul_f32_e32 v5, v5, v1
	v_mul_f32_e32 v6, v6, v2
	v_mul_f32_e32 v7, v7, v3
	v_mul_f32_e32 v246, v246, v4
	v_exp_f32_e32 v5, v5
	v_exp_f32_e32 v6, v6
	v_exp_f32_e32 v7, v7
	v_exp_f32_e32 v246, v246
	v_add_f32_e32 v5, 1.0, v5
	v_add_f32_e32 v6, 1.0, v6
	v_add_f32_e32 v7, 1.0, v7
	v_add_f32_e32 v246, 1.0, v246
	v_rcp_f32_e32 v5, v5
	v_rcp_f32_e32 v6, v6
	v_rcp_f32_e32 v7, v7
	v_rcp_f32_e32 v246, v246
	v_fma_f32 v1, -v1, v5, v1
	v_fma_f32 v2, -v2, v6, v2
	v_fma_f32 v3, -v3, v7, v3
	v_fma_f32 v4, -v4, v246, v4
	v_cvt_pk_bf16_f32 v1, v1, v1
	v_cvt_pk_bf16_f32 v2, v2, v2
	v_cvt_pk_bf16_f32 v3, v3, v3
	v_cvt_pk_bf16_f32 v4, v4, v4
	global_store_short v198, v1, s[28:29] offset:-4096
	global_store_short v198, v2, s[28:29] offset:-2048
	global_store_short v198, v3, s[28:29] offset:0
	global_store_short v198, v4, s[28:29] offset:2048
	s_add_u32 s28, s28, 0x8000
	s_addc_u32 s29, s29, 0
	v_fma_f32 v194, -v73, v193, v160
	v_fma_f32 v195, v73, v192, v176
	v_fma_f32 v160, v72, v192, v194
	v_fma_f32 v176, v72, v193, v195
	ds_write_addtid_b32 v160 offset:0
	ds_write_addtid_b32 v176 offset:256
	v_fma_f32 v194, -v73, v176, v161
	v_fma_f32 v195, v73, v160, v177
	v_fma_f32 v161, v72, v160, v194
	v_fma_f32 v177, v72, v176, v195
	ds_write_addtid_b32 v161 offset:528
	ds_write_addtid_b32 v177 offset:784
	v_fma_f32 v194, -v73, v177, v162
	v_fma_f32 v195, v73, v161, v178
	v_fma_f32 v162, v72, v161, v194
	v_fma_f32 v178, v72, v177, v195
	ds_write_addtid_b32 v162 offset:1056
	ds_write_addtid_b32 v178 offset:1312
	v_fma_f32 v194, -v73, v178, v163
	v_fma_f32 v195, v73, v162, v179
	v_fma_f32 v163, v72, v162, v194
	v_fma_f32 v179, v72, v178, v195
	ds_write_addtid_b32 v163 offset:1584
	ds_write_addtid_b32 v179 offset:1840
	v_fma_f32 v194, -v73, v179, v164
	v_fma_f32 v195, v73, v163, v180
	v_fma_f32 v164, v72, v163, v194
	v_fma_f32 v180, v72, v179, v195
	ds_write_addtid_b32 v164 offset:2112
	ds_write_addtid_b32 v180 offset:2368
	v_fma_f32 v194, -v73, v180, v165
	v_fma_f32 v195, v73, v164, v181
	v_fma_f32 v165, v72, v164, v194
	v_fma_f32 v181, v72, v180, v195
	ds_write_addtid_b32 v165 offset:2640
	ds_write_addtid_b32 v181 offset:2896
	v_fma_f32 v194, -v73, v181, v166
	v_fma_f32 v195, v73, v165, v182
	v_fma_f32 v166, v72, v165, v194
	v_fma_f32 v182, v72, v181, v195
	ds_write_addtid_b32 v166 offset:3168
	ds_write_addtid_b32 v182 offset:3424
	v_fma_f32 v194, -v73, v182, v167
	v_fma_f32 v195, v73, v166, v183
	v_fma_f32 v167, v72, v166, v194
	v_fma_f32 v183, v72, v182, v195
	ds_write_addtid_b32 v167 offset:3696
	ds_write_addtid_b32 v183 offset:3952
	v_fma_f32 v194, -v73, v183, v168
	v_fma_f32 v195, v73, v167, v184
	v_fma_f32 v168, v72, v167, v194
	v_fma_f32 v184, v72, v183, v195
	ds_write_addtid_b32 v168 offset:4224
	ds_write_addtid_b32 v184 offset:4480
	v_fma_f32 v194, -v73, v184, v169
	v_fma_f32 v195, v73, v168, v185
	v_fma_f32 v169, v72, v168, v194
	v_fma_f32 v185, v72, v184, v195
	ds_write_addtid_b32 v169 offset:4752
	ds_write_addtid_b32 v185 offset:5008
	v_fma_f32 v194, -v73, v185, v170
	v_fma_f32 v195, v73, v169, v186
	v_fma_f32 v170, v72, v169, v194
	v_fma_f32 v186, v72, v185, v195
	ds_write_addtid_b32 v170 offset:5280
	ds_write_addtid_b32 v186 offset:5536
	v_fma_f32 v194, -v73, v186, v171
	v_fma_f32 v195, v73, v170, v187
	v_fma_f32 v171, v72, v170, v194
	v_fma_f32 v187, v72, v186, v195
	ds_write_addtid_b32 v171 offset:5808
	ds_write_addtid_b32 v187 offset:6064
	v_fma_f32 v194, -v73, v187, v172
	v_fma_f32 v195, v73, v171, v188
	v_fma_f32 v172, v72, v171, v194
	v_fma_f32 v188, v72, v187, v195
	ds_write_addtid_b32 v172 offset:6336
	ds_write_addtid_b32 v188 offset:6592
	v_fma_f32 v194, -v73, v188, v173
	v_fma_f32 v195, v73, v172, v189
	v_fma_f32 v173, v72, v172, v194
	v_fma_f32 v189, v72, v188, v195
	ds_write_addtid_b32 v173 offset:6864
	ds_write_addtid_b32 v189 offset:7120
	v_fma_f32 v194, -v73, v189, v174
	v_fma_f32 v195, v73, v173, v190
	v_fma_f32 v174, v72, v173, v194
	v_fma_f32 v190, v72, v189, v195
	ds_write_addtid_b32 v174 offset:7392
	ds_write_addtid_b32 v190 offset:7648
	v_fma_f32 v194, -v73, v190, v175
	v_fma_f32 v195, v73, v174, v191
	v_fma_f32 v175, v72, v174, v194
	v_fma_f32 v191, v72, v190, v195
	ds_write_addtid_b32 v175 offset:7920
	ds_write_addtid_b32 v191 offset:8176
	v_mov_b32_e32 v192, v175
	v_mov_b32_e32 v193, v191
	ds_read_b128 v[208:211], v77 offset:0
	ds_read_b128 v[212:215], v77 offset:64
	ds_read_b128 v[216:219], v77 offset:128
	ds_read_b128 v[220:223], v77 offset:192
	ds_read_b128 v[224:227], v77 offset:256
	ds_read_b128 v[228:231], v77 offset:320
	ds_read_b128 v[232:235], v77 offset:384
	ds_read_b128 v[236:239], v77 offset:448
	s_waitcnt lgkmcnt(7)
; DI unsigned pk2(float a, float b) { f32x2_t v = {a, b}; return __builtin_bit_cast(unsigned, __builtin_convertvector(v, bf16x2_t)); }
; DI float gelu_tanh(float v) { const float z = 0.7978845608028654f * (v + 0.044715f * v * v * v); const float th = 1.0f - 2.0f * __builtin_amdgcn_rcpf(__builtin_amdgcn_exp2f(2.8853900817779268f * z) + 1.0f); return 0.5f * v * (1.0f + th); }
; DI void s5_pass3_item(const Params& P, int bitem, unsigned char* smem) {
;     ...
;         for (int i = 0; i < 32; ++i) { const float a = xs[(4 * i + q) * 17 + r]; ya[i & 3] = __builtin_amdgcn_mfma_f32_16x16x4f32(a, cB[i], ya[i & 3], 0, 0, 0); }
;         const f32x4 y = (ya[0] + ya[1]) + (ya[2] + ya[3]);
; #pragma unroll
;         for (int j = 0; j < 4; ++j) { const int tl = sub * 16 + 4 * q + j; const float v = y[j] + dsk * uv[j];
;             HG[(size_t)(b * TT + ch * 64 + tl) * 1024 + grp * 16 + r] = (bf16_t)(pk2(gelu_tanh(v), 0.f) & 0xffffu); }
;         asm volatile("s_waitcnt lgkmcnt(0)" ::: "memory");
;     }
; }
	v_mfma_f32_16x16x4_f32 v[200:203], v208, v40, 0
	v_mfma_f32_16x16x4_f32 v[240:243], v209, v41, 0
	v_mfma_f32_16x16x4_f32 v[200:203], v210, v42, v[200:203]
	v_mfma_f32_16x16x4_f32 v[240:243], v211, v43, v[240:243]
	s_waitcnt lgkmcnt(6)
	v_mfma_f32_16x16x4_f32 v[200:203], v212, v44, v[200:203]
	v_mfma_f32_16x16x4_f32 v[240:243], v213, v45, v[240:243]
	v_mfma_f32_16x16x4_f32 v[200:203], v214, v46, v[200:203]
	v_mfma_f32_16x16x4_f32 v[240:243], v215, v47, v[240:243]
	s_waitcnt lgkmcnt(5)
	v_mfma_f32_16x16x4_f32 v[200:203], v216, v48, v[200:203]
	v_mfma_f32_16x16x4_f32 v[240:243], v217, v49, v[240:243]
	v_mfma_f32_16x16x4_f32 v[200:203], v218, v50, v[200:203]
	v_mfma_f32_16x16x4_f32 v[240:243], v219, v51, v[240:243]
	s_waitcnt lgkmcnt(4)
	v_mfma_f32_16x16x4_f32 v[200:203], v220, v52, v[200:203]
	v_mfma_f32_16x16x4_f32 v[240:243], v221, v53, v[240:243]
	v_mfma_f32_16x16x4_f32 v[200:203], v222, v54, v[200:203]
	v_mfma_f32_16x16x4_f32 v[240:243], v223, v55, v[240:243]
	s_waitcnt lgkmcnt(3)
	v_mfma_f32_16x16x4_f32 v[200:203], v224, v56, v[200:203]
	v_mfma_f32_16x16x4_f32 v[240:243], v225, v57, v[240:243]
	v_mfma_f32_16x16x4_f32 v[200:203], v226, v58, v[200:203]
	v_mfma_f32_16x16x4_f32 v[240:243], v227, v59, v[240:243]
	s_waitcnt lgkmcnt(2)
	v_mfma_f32_16x16x4_f32 v[200:203], v228, v60, v[200:203]
	v_mfma_f32_16x16x4_f32 v[240:243], v229, v61, v[240:243]
	v_mfma_f32_16x16x4_f32 v[200:203], v230, v62, v[200:203]
	v_mfma_f32_16x16x4_f32 v[240:243], v231, v63, v[240:243]
	s_waitcnt lgkmcnt(1)
	v_mfma_f32_16x16x4_f32 v[200:203], v232, v64, v[200:203]
	v_mfma_f32_16x16x4_f32 v[240:243], v233, v65, v[240:243]
	v_mfma_f32_16x16x4_f32 v[200:203], v234, v66, v[200:203]
	v_mfma_f32_16x16x4_f32 v[240:243], v235, v67, v[240:243]
	s_waitcnt lgkmcnt(0)
	v_mfma_f32_16x16x4_f32 v[200:203], v236, v68, v[200:203]
	v_mfma_f32_16x16x4_f32 v[240:243], v237, v69, v[240:243]
	v_mfma_f32_16x16x4_f32 v[200:203], v238, v70, v[200:203]
	v_mfma_f32_16x16x4_f32 v[240:243], v239, v71, v[240:243]
	s_nop 9
	v_add_f32_e32 v1, v200, v240
	v_add_f32_e32 v2, v201, v241
	v_add_f32_e32 v3, v202, v242
	v_add_f32_e32 v4, v203, v243
	v_fmac_f32_e32 v1, v76, v116
	v_fmac_f32_e32 v2, v76, v117
	v_fmac_f32_e32 v3, v76, v118
	v_fmac_f32_e32 v4, v76, v119
	v_mul_f32_e32 v5, v1, v1
	v_mul_f32_e32 v6, v2, v2
	v_mul_f32_e32 v7, v3, v3
	v_mul_f32_e32 v246, v4, v4
	v_fma_f32 v5, v5, v80, v205
	v_fma_f32 v6, v6, v80, v205
	v_fma_f32 v7, v7, v80, v205
	v_fma_f32 v246, v246, v80, v205
	v_mul_f32_e32 v5, v5, v1
	v_mul_f32_e32 v6, v6, v2
	v_mul_f32_e32 v7, v7, v3
	v_mul_f32_e32 v246, v246, v4
	v_exp_f32_e32 v5, v5
	v_exp_f32_e32 v6, v6
	v_exp_f32_e32 v7, v7
	v_exp_f32_e32 v246, v246
	v_add_f32_e32 v5, 1.0, v5
	v_add_f32_e32 v6, 1.0, v6
	v_add_f32_e32 v7, 1.0, v7
	v_add_f32_e32 v246, 1.0, v246
	v_rcp_f32_e32 v5, v5
	v_rcp_f32_e32 v6, v6
	v_rcp_f32_e32 v7, v7
	v_rcp_f32_e32 v246, v246
	v_fma_f32 v1, -v1, v5, v1
	v_fma_f32 v2, -v2, v6, v2
	v_fma_f32 v3, -v3, v7, v3
	v_fma_f32 v4, -v4, v246, v4
	v_cvt_pk_bf16_f32 v1, v1, v1
	v_cvt_pk_bf16_f32 v2, v2, v2
	v_cvt_pk_bf16_f32 v3, v3, v3
	v_cvt_pk_bf16_f32 v4, v4, v4
	global_store_short v198, v1, s[28:29] offset:-4096
	global_store_short v198, v2, s[28:29] offset:-2048
	global_store_short v198, v3, s[28:29] offset:0
	global_store_short v198, v4, s[28:29] offset:2048
	s_add_u32 s26, s26, 0x400000
	s_addc_u32 s27, s27, 0
	s_xor_b32 s20, s20, 0x4000
	s_add_i32 s19, s19, 1
	s_cmp_lt_u32 s19, 8
	s_cbranch_scc1 .Ls5n_round
	s_waitcnt vmcnt(0) lgkmcnt(0)
	s_barrier
	s_branch .LBB0_727
